# GEMM tile head zeroes only the first phase's accumulators (v_mov_b64), the other 96 are zeroed inside the first K-iteration under the LDS reads
# speedup vs baseline: 1.0159x; 1.0013x over previous
; #define PG8_STAGE(bufoff, gbase, voff) do { _Pragma("unroll") for (int _i = 0; _i < 2; ++_i) \
;         __builtin_amdgcn_global_load_lds((const unsigned*)((const char*)(gbase) + (voff)[_i]), (LAS unsigned*)(lds + (bufoff) + ldsw + _i * 8192), 16, 0, 0); } while (0)
; #define PG8_LDA(dst, b, h) do { _Pragma("unroll") for (int m = 0; m < 4; ++m) _Pragma("unroll") for (int k = 0; k < 2; ++k) dst[m][k] = *(const LAS bf16x8*)(lds + PG8_SA(b, h) + aoff + m * 2048 + k * 1024); } while (0)
; #define PG8_LDB(dst, b, h) do { _Pragma("unroll") for (int n = 0; n < 2; ++n) _Pragma("unroll") for (int k = 0; k < 2; ++k) dst[n][k] = *(const LAS bf16x8*)(lds + PG8_SB(b, h) + boff + n * 2048 + k * 1024); } while (0)
; #define PG8_MMA(ai, bj, At, Bt) do { __builtin_amdgcn_s_setprio(1); _Pragma("unroll") for (int m = 0; m < 4; ++m) _Pragma("unroll") for (int n = 0; n < 2; ++n) _Pragma("unroll") for (int k = 0; k < 2; ++k) \
;         acc[ai][bj][m][n] = __builtin_amdgcn_mfma_f32_16x16x32_bf16(Bt[n][k], At[m][k], acc[ai][bj][m][n], 0, 0, 0); __builtin_amdgcn_s_setprio(0); } while (0)
; #define PG8_BAR __builtin_amdgcn_s_barrier()
; template <class Epi, class Sched>
; __device__ __forceinline__ void gemm_phase(LAS unsigned char* lds, const Gemm g, const Sched& S, const Epi& E) {
;     ...
;         const bool has_next = S.next(ui + 1, nxt);
;         const char* nA = has_next ? (const char*)g.A + (size_t)nxt.pm * tstep : cA; const char* nB = has_next ? (const char*)g.Bt + (size_t)nxt.pn * tstep : cB;
;         for (int t = 0; t < nt; t += 2) {
;             const bool last = (t == nt - 2);
;             const char* a1 = cA + (size_t)(t + 1) * kstep;
;             const char* a2 = last ? nA : cA + (size_t)(t + 2) * kstep; const char* b2 = last ? nB : cB + (size_t)(t + 2) * kstep;
;             const char* a3 = a2 + kstep; const char* b3 = b2 + kstep;
;             if (last && has_next) S.a_ready(nxt);
;             PG8_LDB(B0, 0, 0); PG8_SCHED; PG8_LDA(At, 0, 0); PG8_STAGE(PG8_SA(1, 1), a1 + hstep, voffA);
;             PG8_WAIT_L(8); PG8_BAR; PG8_WAIT_L(0); PG8_MMA(0, 0, At, B0); PG8_BAR; PG8_SCHED;
;     ...
;         for (int a = 0; a < 2; ++a)
; #pragma unroll
;             for (int b = 0; b < 2; ++b)
; #pragma unroll
;                 for (int m = 0; m < 4; ++m)
; #pragma unroll
;                     for (int n = 0; n < 2; ++n) acc[a][b][m][n] = (f32x4){0.f, 0.f, 0.f, 0.f};
.LBB0_186:
	s_ashr_i32 s41, s40, 31
	s_lshl_b64 s[16:17], s[40:41], 19
	v_cmp_lt_i64_e32 vcc, s[42:43], v[138:139]
	s_add_u32 s42, s76, s16
	s_addc_u32 s43, s77, s17
	s_and_b64 s[16:17], vcc, exec
	s_cselect_b32 s41, s43, s71
	s_cselect_b32 s78, s42, s70
	s_ashr_i32 s1, s0, 31
	s_lshl_b64 s[16:17], s[0:1], 19
	s_add_u32 s88, s6, s16
	s_addc_u32 s89, s7, s17
	s_and_b64 s[16:17], vcc, exec
	s_cselect_b32 s1, s89, s67
	s_cselect_b32 s16, s88, s66
	s_add_u32 s72, s70, 0x40080
	s_addc_u32 s73, s71, 0
	s_add_u32 s17, s66, 0x100
	v_mov_b64_e32 v[78:79], 0
	v_mov_b64_e32 v[80:81], 0
	v_mov_b64_e32 v[86:87], 0
	v_mov_b64_e32 v[88:89], 0
	v_mov_b64_e32 v[94:95], 0
	v_mov_b64_e32 v[96:97], 0
	v_mov_b64_e32 v[102:103], 0
	v_mov_b64_e32 v[104:105], 0
	v_mov_b64_e32 v[110:111], 0
	v_mov_b64_e32 v[112:113], 0
	v_mov_b64_e32 v[118:119], 0
	v_mov_b64_e32 v[120:121], 0
	v_mov_b64_e32 v[122:123], 0
	v_mov_b64_e32 v[124:125], 0
	v_mov_b64_e32 v[126:127], 0
	v_mov_b64_e32 v[128:129], 0
	s_addc_u32 s18, s67, 0
	s_mov_b32 s19, -2
.LBB0_187:
	s_add_u32 s20, s72, 0xfffc0080
	s_addc_u32 s21, s73, -1
	s_add_i32 s22, 16, 0x10000
	v_add_u32_e32 v153, s22, v154
	ds_read_b128 v[156:159], v153
	ds_read_b128 v[160:163], v153 offset:1024
	ds_read_b128 v[164:167], v153 offset:2048
	ds_read_b128 v[168:171], v153 offset:3072
	s_cmp_eq_u32 s19, 12
	s_cselect_b32 s71, s41, s21
	s_cselect_b32 s70, s78, s20
	s_cselect_b32 s67, s1, s18
	s_cselect_b32 s66, s16, s17
	v_lshl_add_u64 v[216:217], s[72:73], 0, v[148:149]
	s_add_i32 m0, s9, 0xc000
	ds_read_b128 v[172:175], v155
	ds_read_b128 v[188:191], v155 offset:1024
	ds_read_b128 v[192:195], v155 offset:2048
	ds_read_b128 v[196:199], v155 offset:3072
	ds_read_b128 v[200:203], v155 offset:4096
	ds_read_b128 v[204:207], v155 offset:5120
	ds_read_b128 v[208:211], v155 offset:6144
	ds_read_b128 v[212:215], v155 offset:7168
	global_load_lds_dwordx4 v[216:217], off
	v_lshl_add_u64 v[216:217], s[72:73], 0, v[150:151]
	s_add_i32 m0, s9, 0xe000
	s_nop 0
	global_load_lds_dwordx4 v[216:217], off
	s_cmp_lg_u32 s19, -2
	s_cbranch_scc1 .Lzd184
	v_mov_b64_e32 v[66:67], 0
	v_mov_b64_e32 v[68:69], 0
	v_mov_b64_e32 v[70:71], 0
	v_mov_b64_e32 v[72:73], 0
	v_mov_b64_e32 v[74:75], 0
	v_mov_b64_e32 v[76:77], 0
	v_mov_b64_e32 v[82:83], 0
	v_mov_b64_e32 v[84:85], 0
	v_mov_b64_e32 v[90:91], 0
	v_mov_b64_e32 v[92:93], 0
	v_mov_b64_e32 v[98:99], 0
	v_mov_b64_e32 v[100:101], 0
	v_mov_b64_e32 v[106:107], 0
	v_mov_b64_e32 v[108:109], 0
	v_mov_b64_e32 v[114:115], 0
	v_mov_b64_e32 v[116:117], 0
	v_mov_b64_e32 v[18:19], 0
	v_mov_b64_e32 v[20:21], 0
	v_mov_b64_e32 v[22:23], 0
	v_mov_b64_e32 v[24:25], 0
	v_mov_b64_e32 v[34:35], 0
	v_mov_b64_e32 v[36:37], 0
	v_mov_b64_e32 v[38:39], 0
	v_mov_b64_e32 v[40:41], 0
	v_mov_b64_e32 v[50:51], 0
	v_mov_b64_e32 v[52:53], 0
	v_mov_b64_e32 v[54:55], 0
	v_mov_b64_e32 v[56:57], 0
	v_mov_b64_e32 v[58:59], 0
	v_mov_b64_e32 v[60:61], 0
	v_mov_b64_e32 v[62:63], 0
	v_mov_b64_e32 v[64:65], 0
	v_mov_b64_e32 v[0:1], 0
	v_mov_b64_e32 v[2:3], 0
	v_mov_b64_e32 v[4:5], 0
	v_mov_b64_e32 v[6:7], 0
	v_mov_b64_e32 v[10:11], 0
	v_mov_b64_e32 v[12:13], 0
	v_mov_b64_e32 v[14:15], 0
	v_mov_b64_e32 v[16:17], 0
	v_mov_b64_e32 v[26:27], 0
	v_mov_b64_e32 v[28:29], 0
	v_mov_b64_e32 v[30:31], 0
	v_mov_b64_e32 v[32:33], 0
	v_mov_b64_e32 v[42:43], 0
	v_mov_b64_e32 v[44:45], 0
	v_mov_b64_e32 v[46:47], 0
	v_mov_b64_e32 v[48:49], 0
.Lzd184:
	s_waitcnt lgkmcnt(8)
	s_barrier
	s_waitcnt lgkmcnt(0)
	s_setprio 1
	s_waitcnt lgkmcnt(0)
	v_mfma_f32_16x16x32_bf16 v[126:129], v[156:159], v[172:175], v[126:129]
	v_mfma_f32_16x16x32_bf16 v[122:125], v[164:167], v[172:175], v[122:125]
	v_mfma_f32_16x16x32_bf16 v[118:121], v[156:159], v[192:195], v[118:121]
	v_mfma_f32_16x16x32_bf16 v[110:113], v[164:167], v[192:195], v[110:113]
	v_mfma_f32_16x16x32_bf16 v[102:105], v[156:159], v[200:203], v[102:105]
	v_mfma_f32_16x16x32_bf16 v[94:97], v[164:167], v[200:203], v[94:97]
	v_mfma_f32_16x16x32_bf16 v[86:89], v[156:159], v[208:211], v[86:89]
	v_mfma_f32_16x16x32_bf16 v[78:81], v[164:167], v[208:211], v[78:81]
	v_mfma_f32_16x16x32_bf16 v[126:129], v[160:163], v[188:191], v[126:129]
	v_mfma_f32_16x16x32_bf16 v[122:125], v[168:171], v[188:191], v[122:125]
	v_mfma_f32_16x16x32_bf16 v[118:121], v[160:163], v[196:199], v[118:121]
	v_mfma_f32_16x16x32_bf16 v[110:113], v[168:171], v[196:199], v[110:113]
	v_mfma_f32_16x16x32_bf16 v[102:105], v[160:163], v[204:207], v[102:105]
	v_mfma_f32_16x16x32_bf16 v[94:97], v[168:171], v[204:207], v[94:97]
	v_mfma_f32_16x16x32_bf16 v[86:89], v[160:163], v[212:215], v[86:89]
	v_mfma_f32_16x16x32_bf16 v[78:81], v[168:171], v[212:215], v[78:81]
	s_setprio 0
	s_barrier
	s_add_i32 s23, 16, 0x14000
	s_add_i32 s20, s22, s8
	v_add_u32_e32 v153, s23, v154
	v_lshl_add_u64 v[232:233], s[66:67], 0, v[144:145]
	s_mov_b32 m0, s20
	ds_read_b128 v[216:219], v153
	ds_read_b128 v[220:223], v153 offset:1024
	ds_read_b128 v[224:227], v153 offset:2048
	ds_read_b128 v[228:231], v153 offset:3072
	global_load_lds_dwordx4 v[232:233], off
	v_lshl_add_u64 v[234:235], s[66:67], 0, v[140:141]
	s_add_i32 m0, s20, 0x2000
	s_nop 0
	global_load_lds_dwordx4 v[234:235], off
	s_barrier
; #define PG8_STAGE(bufoff, gbase, voff) do { _Pragma("unroll") for (int _i = 0; _i < 2; ++_i) \
;         __builtin_amdgcn_global_load_lds((const unsigned*)((const char*)(gbase) + (voff)[_i]), (LAS unsigned*)(lds + (bufoff) + ldsw + _i * 8192), 16, 0, 0); } while (0)
; #define PG8_LDA(dst, b, h) do { _Pragma("unroll") for (int m = 0; m < 4; ++m) _Pragma("unroll") for (int k = 0; k < 2; ++k) dst[m][k] = *(const LAS bf16x8*)(lds + PG8_SA(b, h) + aoff + m * 2048 + k * 1024); } while (0)
; #define PG8_LDB(dst, b, h) do { _Pragma("unroll") for (int n = 0; n < 2; ++n) _Pragma("unroll") for (int k = 0; k < 2; ++k) dst[n][k] = *(const LAS bf16x8*)(lds + PG8_SB(b, h) + boff + n * 2048 + k * 1024); } while (0)
; #define PG8_MMA(ai, bj, At, Bt) do { __builtin_amdgcn_s_setprio(1); _Pragma("unroll") for (int m = 0; m < 4; ++m) _Pragma("unroll") for (int n = 0; n < 2; ++n) _Pragma("unroll") for (int k = 0; k < 2; ++k) \
;         acc[ai][bj][m][n] = __builtin_amdgcn_mfma_f32_16x16x32_bf16(Bt[n][k], At[m][k], acc[ai][bj][m][n], 0, 0, 0); __builtin_amdgcn_s_setprio(0); } while (0)
; #define PG8_WAIT_V(n) asm volatile("s_waitcnt vmcnt(" #n ")" ::: "memory")
; #define PG8_WAIT_L(n) asm volatile("s_waitcnt lgkmcnt(" #n ")" ::: "memory")
; #define PG8_BAR __builtin_amdgcn_s_barrier()
; #define PG8_SCHED __builtin_amdgcn_sched_barrier(0)
; template <class Epi, class Sched>
; __device__ __forceinline__ void gemm_phase(LAS unsigned char* lds, const Gemm g, const Sched& S, const Epi& E) {
;     ...
;             PG8_WAIT_L(8); PG8_BAR; PG8_WAIT_L(0); PG8_MMA(0, 0, At, B0); PG8_BAR; PG8_SCHED;
;             PG8_LDB(B1, 0, 1); PG8_STAGE(PG8_SB(0, 0), b2, voffB);
;             PG8_BAR; PG8_WAIT_L(0); PG8_MMA(0, 1, At, B1); PG8_BAR;
;             PG8_LDA(At, 0, 1); PG8_STAGE(PG8_SA(0, 0), a2, voffA);
;             PG8_BAR; PG8_WAIT_L(0); PG8_MMA(1, 0, At, B0); PG8_BAR; PG8_SCHED;
;             PG8_STAGE(PG8_SB(0, 1), b2 + hstep, voffB);
;             PG8_WAIT_V(6); PG8_BAR; PG8_MMA(1, 1, At, B1); PG8_BAR;
;             PG8_LDB(B0, 1, 0); PG8_SCHED; PG8_LDA(At, 1, 0); PG8_STAGE(PG8_SA(0, 1), a2 + hstep, voffA);
	s_waitcnt lgkmcnt(0)
	s_setprio 1
	s_waitcnt lgkmcnt(0)
	v_mfma_f32_16x16x32_bf16 v[114:117], v[216:219], v[172:175], v[114:117]
	v_mfma_f32_16x16x32_bf16 v[106:109], v[224:227], v[172:175], v[106:109]
	v_mfma_f32_16x16x32_bf16 v[98:101], v[216:219], v[192:195], v[98:101]
	v_mfma_f32_16x16x32_bf16 v[90:93], v[224:227], v[192:195], v[90:93]
	v_mfma_f32_16x16x32_bf16 v[82:85], v[216:219], v[200:203], v[82:85]
	v_mfma_f32_16x16x32_bf16 v[74:77], v[224:227], v[200:203], v[74:77]
	v_mfma_f32_16x16x32_bf16 v[70:73], v[216:219], v[208:211], v[70:73]
	v_mfma_f32_16x16x32_bf16 v[66:69], v[224:227], v[208:211], v[66:69]
	v_mfma_f32_16x16x32_bf16 v[114:117], v[220:223], v[188:191], v[114:117]
	v_mfma_f32_16x16x32_bf16 v[106:109], v[228:231], v[188:191], v[106:109]
	v_mfma_f32_16x16x32_bf16 v[98:101], v[220:223], v[196:199], v[98:101]
	v_mfma_f32_16x16x32_bf16 v[90:93], v[228:231], v[196:199], v[90:93]
	v_mfma_f32_16x16x32_bf16 v[82:85], v[220:223], v[204:207], v[82:85]
	v_mfma_f32_16x16x32_bf16 v[74:77], v[228:231], v[204:207], v[74:77]
	v_mfma_f32_16x16x32_bf16 v[70:73], v[220:223], v[212:215], v[70:73]
	v_mfma_f32_16x16x32_bf16 v[66:69], v[228:231], v[212:215], v[66:69]
	s_setprio 0
	s_mov_b32 m0, s9
	v_lshl_add_u64 v[236:237], s[70:71], 0, v[146:147]
	s_barrier
	ds_read_b128 v[172:175], v155 offset:16384
	ds_read_b128 v[188:191], v155 offset:17408
	ds_read_b128 v[192:195], v155 offset:18432
	ds_read_b128 v[196:199], v155 offset:19456
	ds_read_b128 v[200:203], v155 offset:20480
	ds_read_b128 v[204:207], v155 offset:21504
	ds_read_b128 v[208:211], v155 offset:22528
	ds_read_b128 v[212:215], v155 offset:23552
	global_load_lds_dwordx4 v[236:237], off
	v_lshl_add_u64 v[238:239], s[70:71], 0, v[142:143]
	s_mov_b32 m0, s10
	s_nop 0
	global_load_lds_dwordx4 v[238:239], off
	s_barrier
	s_waitcnt lgkmcnt(0)
	s_setprio 1
	s_waitcnt lgkmcnt(0)
	v_mfma_f32_16x16x32_bf16 v[62:65], v[156:159], v[172:175], v[62:65]
	v_mfma_f32_16x16x32_bf16 v[58:61], v[164:167], v[172:175], v[58:61]
	v_mfma_f32_16x16x32_bf16 v[54:57], v[156:159], v[192:195], v[54:57]
	v_mfma_f32_16x16x32_bf16 v[50:53], v[164:167], v[192:195], v[50:53]
	v_mfma_f32_16x16x32_bf16 v[38:41], v[156:159], v[200:203], v[38:41]
	v_mfma_f32_16x16x32_bf16 v[34:37], v[164:167], v[200:203], v[34:37]
	v_mfma_f32_16x16x32_bf16 v[22:25], v[156:159], v[208:211], v[22:25]
	v_mfma_f32_16x16x32_bf16 v[18:21], v[164:167], v[208:211], v[18:21]
	v_mfma_f32_16x16x32_bf16 v[62:65], v[160:163], v[188:191], v[62:65]
	v_mfma_f32_16x16x32_bf16 v[58:61], v[168:171], v[188:191], v[58:61]
	v_mfma_f32_16x16x32_bf16 v[54:57], v[160:163], v[196:199], v[54:57]
	v_mfma_f32_16x16x32_bf16 v[50:53], v[168:171], v[196:199], v[50:53]
	v_mfma_f32_16x16x32_bf16 v[38:41], v[160:163], v[204:207], v[38:41]
	v_mfma_f32_16x16x32_bf16 v[34:37], v[168:171], v[204:207], v[34:37]
	v_mfma_f32_16x16x32_bf16 v[22:25], v[160:163], v[212:215], v[22:25]
	v_mfma_f32_16x16x32_bf16 v[18:21], v[168:171], v[212:215], v[18:21]
	s_setprio 0
	s_barrier
	s_add_u32 s20, s66, 0x40000
	s_addc_u32 s21, s67, 0
	s_add_i32 s22, s23, s8
	v_lshl_add_u64 v[156:157], s[20:21], 0, v[144:145]
	s_mov_b32 m0, s22
	s_nop 0
	global_load_lds_dwordx4 v[156:157], off
	v_lshl_add_u64 v[156:157], s[20:21], 0, v[140:141]
	s_add_i32 m0, s22, 0x2000
	s_nop 0
	global_load_lds_dwordx4 v[156:157], off
	s_waitcnt vmcnt(6)
	s_barrier
	s_setprio 1
	v_mfma_f32_16x16x32_bf16 v[46:49], v[216:219], v[172:175], v[46:49]
	v_mfma_f32_16x16x32_bf16 v[42:45], v[224:227], v[172:175], v[42:45]
	v_mfma_f32_16x16x32_bf16 v[30:33], v[216:219], v[192:195], v[30:33]
	v_mfma_f32_16x16x32_bf16 v[26:29], v[224:227], v[192:195], v[26:29]
	v_mfma_f32_16x16x32_bf16 v[14:17], v[216:219], v[200:203], v[14:17]
	v_mfma_f32_16x16x32_bf16 v[10:13], v[224:227], v[200:203], v[10:13]
	v_mfma_f32_16x16x32_bf16 v[4:7], v[216:219], v[208:211], v[4:7]
	v_mfma_f32_16x16x32_bf16 v[0:3], v[224:227], v[208:211], v[0:3]
	v_mfma_f32_16x16x32_bf16 v[46:49], v[220:223], v[188:191], v[46:49]
	v_mfma_f32_16x16x32_bf16 v[42:45], v[228:231], v[188:191], v[42:45]
	v_mfma_f32_16x16x32_bf16 v[30:33], v[220:223], v[196:199], v[30:33]
	v_mfma_f32_16x16x32_bf16 v[26:29], v[228:231], v[196:199], v[26:29]
	v_mfma_f32_16x16x32_bf16 v[14:17], v[220:223], v[204:207], v[14:17]
	v_mfma_f32_16x16x32_bf16 v[10:13], v[228:231], v[204:207], v[10:13]
	v_mfma_f32_16x16x32_bf16 v[4:7], v[220:223], v[212:215], v[4:7]
	v_mfma_f32_16x16x32_bf16 v[0:3], v[228:231], v[212:215], v[0:3]
	s_setprio 0
	s_add_i32 s22, 16, 0x18000
	v_add_u32_e32 v153, s22, v154
	s_barrier
	ds_read_b128 v[156:159], v153
	ds_read_b128 v[160:163], v153 offset:1024
	ds_read_b128 v[164:167], v153 offset:2048
	ds_read_b128 v[168:171], v153 offset:3072
	s_add_u32 s20, s70, 0x40000
	s_addc_u32 s21, s71, 0
	s_mov_b32 m0, s11
	v_lshl_add_u64 v[216:217], s[20:21], 0, v[146:147]
	ds_read_b128 v[172:175], v155 offset:32768
	ds_read_b128 v[188:191], v155 offset:33792
	ds_read_b128 v[192:195], v155 offset:34816
	ds_read_b128 v[196:199], v155 offset:35840
	ds_read_b128 v[200:203], v155 offset:36864
	ds_read_b128 v[204:207], v155 offset:37888
	ds_read_b128 v[208:211], v155 offset:38912
	ds_read_b128 v[212:215], v155 offset:39936
	global_load_lds_dwordx4 v[216:217], off
	v_lshl_add_u64 v[216:217], s[20:21], 0, v[142:143]
	s_mov_b32 m0, s12
	s_nop 0
	global_load_lds_dwordx4 v[216:217], off
	s_waitcnt lgkmcnt(8)
	s_barrier
; #define PG8_STAGE(bufoff, gbase, voff) do { _Pragma("unroll") for (int _i = 0; _i < 2; ++_i) \
;         __builtin_amdgcn_global_load_lds((const unsigned*)((const char*)(gbase) + (voff)[_i]), (LAS unsigned*)(lds + (bufoff) + ldsw + _i * 8192), 16, 0, 0); } while (0)
; #define PG8_LDA(dst, b, h) do { _Pragma("unroll") for (int m = 0; m < 4; ++m) _Pragma("unroll") for (int k = 0; k < 2; ++k) dst[m][k] = *(const LAS bf16x8*)(lds + PG8_SA(b, h) + aoff + m * 2048 + k * 1024); } while (0)
; #define PG8_LDB(dst, b, h) do { _Pragma("unroll") for (int n = 0; n < 2; ++n) _Pragma("unroll") for (int k = 0; k < 2; ++k) dst[n][k] = *(const LAS bf16x8*)(lds + PG8_SB(b, h) + boff + n * 2048 + k * 1024); } while (0)
; #define PG8_MMA(ai, bj, At, Bt) do { __builtin_amdgcn_s_setprio(1); _Pragma("unroll") for (int m = 0; m < 4; ++m) _Pragma("unroll") for (int n = 0; n < 2; ++n) _Pragma("unroll") for (int k = 0; k < 2; ++k) \
;         acc[ai][bj][m][n] = __builtin_amdgcn_mfma_f32_16x16x32_bf16(Bt[n][k], At[m][k], acc[ai][bj][m][n], 0, 0, 0); __builtin_amdgcn_s_setprio(0); } while (0)
; #define PG8_WAIT_V(n) asm volatile("s_waitcnt vmcnt(" #n ")" ::: "memory")
; #define PG8_WAIT_L(n) asm volatile("s_waitcnt lgkmcnt(" #n ")" ::: "memory")
; #define PG8_BAR __builtin_amdgcn_s_barrier()
; #define PG8_SCHED __builtin_amdgcn_sched_barrier(0)
; template <class Epi, class Sched>
; __device__ __forceinline__ void gemm_phase(LAS unsigned char* lds, const Gemm g, const Sched& S, const Epi& E) {
;     ...
;             PG8_WAIT_L(8); PG8_BAR; PG8_WAIT_L(0); PG8_MMA(0, 0, At, B0); PG8_BAR; PG8_SCHED;
;             PG8_LDB(B1, 1, 1); PG8_STAGE(PG8_SB(1, 0), b3, voffB);
;             PG8_BAR; PG8_WAIT_L(0); PG8_MMA(0, 1, At, B1); PG8_BAR;
;             PG8_LDA(At, 1, 1); PG8_STAGE(PG8_SA(1, 0), a3, voffA);
;             PG8_BAR; PG8_WAIT_L(0); PG8_MMA(1, 0, At, B0); PG8_BAR; PG8_SCHED;
;             PG8_STAGE(PG8_SB(1, 1), b3 + hstep, voffB);
;             PG8_WAIT_V(6); PG8_BAR; PG8_MMA(1, 1, At, B1); PG8_BAR;
	s_waitcnt lgkmcnt(0)
	s_setprio 1
	s_waitcnt lgkmcnt(0)
	v_mfma_f32_16x16x32_bf16 v[126:129], v[156:159], v[172:175], v[126:129]
	v_mfma_f32_16x16x32_bf16 v[122:125], v[164:167], v[172:175], v[122:125]
	v_mfma_f32_16x16x32_bf16 v[118:121], v[156:159], v[192:195], v[118:121]
	v_mfma_f32_16x16x32_bf16 v[110:113], v[164:167], v[192:195], v[110:113]
	v_mfma_f32_16x16x32_bf16 v[102:105], v[156:159], v[200:203], v[102:105]
	v_mfma_f32_16x16x32_bf16 v[94:97], v[164:167], v[200:203], v[94:97]
	v_mfma_f32_16x16x32_bf16 v[86:89], v[156:159], v[208:211], v[86:89]
	v_mfma_f32_16x16x32_bf16 v[78:81], v[164:167], v[208:211], v[78:81]
	v_mfma_f32_16x16x32_bf16 v[126:129], v[160:163], v[188:191], v[126:129]
	v_mfma_f32_16x16x32_bf16 v[122:125], v[168:171], v[188:191], v[122:125]
	v_mfma_f32_16x16x32_bf16 v[118:121], v[160:163], v[196:199], v[118:121]
	v_mfma_f32_16x16x32_bf16 v[110:113], v[168:171], v[196:199], v[110:113]
	v_mfma_f32_16x16x32_bf16 v[102:105], v[160:163], v[204:207], v[102:105]
	v_mfma_f32_16x16x32_bf16 v[94:97], v[168:171], v[204:207], v[94:97]
	v_mfma_f32_16x16x32_bf16 v[86:89], v[160:163], v[212:215], v[86:89]
	v_mfma_f32_16x16x32_bf16 v[78:81], v[168:171], v[212:215], v[78:81]
	s_setprio 0
	s_barrier
	s_add_i32 s23, 16, 0x1c000
	s_add_i32 s20, s22, s8
	v_add_u32_e32 v153, s23, v154
	v_lshl_add_u64 v[232:233], v[232:233], 0, s[94:95]
	s_mov_b32 m0, s20
	ds_read_b128 v[216:219], v153
	ds_read_b128 v[220:223], v153 offset:1024
	ds_read_b128 v[224:227], v153 offset:2048
	ds_read_b128 v[228:231], v153 offset:3072
	global_load_lds_dwordx4 v[232:233], off
	v_lshl_add_u64 v[232:233], v[234:235], 0, s[94:95]
	s_add_i32 m0, s20, 0x2000
	s_nop 0
	global_load_lds_dwordx4 v[232:233], off
	s_barrier
	s_waitcnt lgkmcnt(0)
	s_setprio 1
	s_waitcnt lgkmcnt(0)
	v_mfma_f32_16x16x32_bf16 v[114:117], v[216:219], v[172:175], v[114:117]
	v_mfma_f32_16x16x32_bf16 v[106:109], v[224:227], v[172:175], v[106:109]
	v_mfma_f32_16x16x32_bf16 v[98:101], v[216:219], v[192:195], v[98:101]
	v_mfma_f32_16x16x32_bf16 v[90:93], v[224:227], v[192:195], v[90:93]
	v_mfma_f32_16x16x32_bf16 v[82:85], v[216:219], v[200:203], v[82:85]
	v_mfma_f32_16x16x32_bf16 v[74:77], v[224:227], v[200:203], v[74:77]
	v_mfma_f32_16x16x32_bf16 v[70:73], v[216:219], v[208:211], v[70:73]
	v_mfma_f32_16x16x32_bf16 v[66:69], v[224:227], v[208:211], v[66:69]
	v_mfma_f32_16x16x32_bf16 v[114:117], v[220:223], v[188:191], v[114:117]
	v_mfma_f32_16x16x32_bf16 v[106:109], v[228:231], v[188:191], v[106:109]
	v_mfma_f32_16x16x32_bf16 v[98:101], v[220:223], v[196:199], v[98:101]
	v_mfma_f32_16x16x32_bf16 v[90:93], v[228:231], v[196:199], v[90:93]
	v_mfma_f32_16x16x32_bf16 v[82:85], v[220:223], v[204:207], v[82:85]
	v_mfma_f32_16x16x32_bf16 v[74:77], v[228:231], v[204:207], v[74:77]
	v_mfma_f32_16x16x32_bf16 v[70:73], v[220:223], v[212:215], v[70:73]
	v_mfma_f32_16x16x32_bf16 v[66:69], v[228:231], v[212:215], v[66:69]
	s_setprio 0
	s_mov_b32 m0, s13
	v_lshl_add_u64 v[232:233], v[236:237], 0, s[94:95]
	s_barrier
	ds_read_b128 v[172:175], v155 offset:49152
	ds_read_b128 v[188:191], v155 offset:50176
	ds_read_b128 v[192:195], v155 offset:51200
	ds_read_b128 v[196:199], v155 offset:52224
	ds_read_b128 v[200:203], v155 offset:53248
	ds_read_b128 v[204:207], v155 offset:54272
	ds_read_b128 v[208:211], v155 offset:55296
	ds_read_b128 v[212:215], v155 offset:56320
	global_load_lds_dwordx4 v[232:233], off
	v_lshl_add_u64 v[232:233], v[238:239], 0, s[94:95]
	s_mov_b32 m0, s74
	s_nop 0
	global_load_lds_dwordx4 v[232:233], off
	s_barrier
	s_waitcnt lgkmcnt(0)
	s_setprio 1
	s_waitcnt lgkmcnt(0)
	v_mfma_f32_16x16x32_bf16 v[62:65], v[156:159], v[172:175], v[62:65]
	v_mfma_f32_16x16x32_bf16 v[58:61], v[164:167], v[172:175], v[58:61]
	v_mfma_f32_16x16x32_bf16 v[54:57], v[156:159], v[192:195], v[54:57]
	v_mfma_f32_16x16x32_bf16 v[50:53], v[164:167], v[192:195], v[50:53]
	v_mfma_f32_16x16x32_bf16 v[38:41], v[156:159], v[200:203], v[38:41]
	v_mfma_f32_16x16x32_bf16 v[34:37], v[164:167], v[200:203], v[34:37]
	v_mfma_f32_16x16x32_bf16 v[22:25], v[156:159], v[208:211], v[22:25]
	v_mfma_f32_16x16x32_bf16 v[18:21], v[164:167], v[208:211], v[18:21]
	v_mfma_f32_16x16x32_bf16 v[62:65], v[160:163], v[188:191], v[62:65]
	v_mfma_f32_16x16x32_bf16 v[58:61], v[168:171], v[188:191], v[58:61]
	v_mfma_f32_16x16x32_bf16 v[54:57], v[160:163], v[196:199], v[54:57]
	v_mfma_f32_16x16x32_bf16 v[50:53], v[168:171], v[196:199], v[50:53]
	v_mfma_f32_16x16x32_bf16 v[38:41], v[160:163], v[204:207], v[38:41]
	v_mfma_f32_16x16x32_bf16 v[34:37], v[168:171], v[204:207], v[34:37]
	v_mfma_f32_16x16x32_bf16 v[22:25], v[160:163], v[212:215], v[22:25]
	v_mfma_f32_16x16x32_bf16 v[18:21], v[168:171], v[212:215], v[18:21]
	s_setprio 0
	s_barrier
	s_add_u32 s20, s66, 0x40080
	s_addc_u32 s21, s67, 0
	s_add_i32 s22, s23, s8
	v_lshl_add_u64 v[156:157], s[20:21], 0, v[144:145]
	s_mov_b32 m0, s22
	s_nop 0
	global_load_lds_dwordx4 v[156:157], off
	v_lshl_add_u64 v[156:157], s[20:21], 0, v[140:141]
	s_add_i32 m0, s22, 0x2000
	s_nop 0
	global_load_lds_dwordx4 v[156:157], off
	s_waitcnt vmcnt(6)
	s_barrier
; __device__ __forceinline__ unsigned pk_bf16(float a, float b) { f32x2 v = {a, b}; bf2_t r = __builtin_convertvector(v, bf2_t); return __builtin_bit_cast(unsigned, r); }
; #define PG8_MMA(ai, bj, At, Bt) do { __builtin_amdgcn_s_setprio(1); _Pragma("unroll") for (int m = 0; m < 4; ++m) _Pragma("unroll") for (int n = 0; n < 2; ++n) _Pragma("unroll") for (int k = 0; k < 2; ++k) \
;         acc[ai][bj][m][n] = __builtin_amdgcn_mfma_f32_16x16x32_bf16(Bt[n][k], At[m][k], acc[ai][bj][m][n], 0, 0, 0); __builtin_amdgcn_s_setprio(0); } while (0)
;     __device__ __forceinline__ void operator()(const f32x4 (&acc)[2][2][4][2], const Unit& u, int wr, int wc, int fr, int fq) const {
;         const int row0 = u.pm * BM + wr * 64 + fr; int colt = u.pn * BM; bf16_t* base = O;
;         if (split_cols) { const int t = colt / split_cols; base += (size_t)t * split_stride; colt -= t * split_cols; }
;         const int col0 = colt + wc * 32 + 8 * fq;
; #pragma unroll
;         for (int ai = 0; ai < 2; ++ai)
; #pragma unroll
;             for (int m = 0; m < 4; ++m) { const int row = row0 + ai * HALF + m * 16;
;                 bf16_t* rowp = slot_stride ? base + (size_t)(colt >> 7) * slot_stride + (size_t)row * 128 + wc * 32 + 8 * fq : base + (size_t)row * ldc + col0;
; #pragma unroll
;                 for (int bj = 0; bj < 2; ++bj) { const f32x4 v0 = acc[ai][bj][m][0], v1 = acc[ai][bj][m][1];
;                     u32x4 w; w.x = pk_bf16(v0[0], v0[1]); w.y = pk_bf16(v0[2], v0[3]); w.z = pk_bf16(v1[0], v1[1]); w.w = pk_bf16(v1[2], v1[3]);
;                     *(u32x4*)(rowp + (slot_stride ? (size_t)bj * slot_stride : (size_t)bj * HALF)) = w; } }
; template <class Epi, class Sched>
; __device__ __forceinline__ void gemm_phase(LAS unsigned char* lds, const Gemm g, const Sched& S, const Epi& E) {
;     ...
;             PG8_WAIT_V(6); PG8_BAR; PG8_MMA(1, 1, At, B1); PG8_BAR;
;         }
;         E(acc, cur, wr, wc, fr, fq); S.done(cur);
;         if (!has_next) break;
; #pragma unroll
;         for (int a = 0; a < 2; ++a)
; #pragma unroll
;             for (int b = 0; b < 2; ++b)
; #pragma unroll
;                 for (int m = 0; m < 4; ++m)
; #pragma unroll
;                     for (int n = 0; n < 2; ++n) acc[a][b][m][n] = (f32x4){0.f, 0.f, 0.f, 0.f};
;         cur = nxt; cA = nA; cB = nB; ++ui;
;     }
;     PG8_WAIT_V(0);
;     if (wr == 0) PG8_BAR;
	s_setprio 1
	v_mfma_f32_16x16x32_bf16 v[46:49], v[216:219], v[172:175], v[46:49]
	v_mfma_f32_16x16x32_bf16 v[42:45], v[224:227], v[172:175], v[42:45]
	v_mfma_f32_16x16x32_bf16 v[30:33], v[216:219], v[192:195], v[30:33]
	v_mfma_f32_16x16x32_bf16 v[26:29], v[224:227], v[192:195], v[26:29]
	v_mfma_f32_16x16x32_bf16 v[14:17], v[216:219], v[200:203], v[14:17]
	v_mfma_f32_16x16x32_bf16 v[10:13], v[224:227], v[200:203], v[10:13]
	v_mfma_f32_16x16x32_bf16 v[4:7], v[216:219], v[208:211], v[4:7]
	v_mfma_f32_16x16x32_bf16 v[0:3], v[224:227], v[208:211], v[0:3]
	v_mfma_f32_16x16x32_bf16 v[46:49], v[220:223], v[188:191], v[46:49]
	v_mfma_f32_16x16x32_bf16 v[42:45], v[228:231], v[188:191], v[42:45]
	v_mfma_f32_16x16x32_bf16 v[30:33], v[220:223], v[196:199], v[30:33]
	v_mfma_f32_16x16x32_bf16 v[26:29], v[228:231], v[196:199], v[26:29]
	v_mfma_f32_16x16x32_bf16 v[14:17], v[220:223], v[204:207], v[14:17]
	v_mfma_f32_16x16x32_bf16 v[10:13], v[228:231], v[204:207], v[10:13]
	v_mfma_f32_16x16x32_bf16 v[4:7], v[220:223], v[212:215], v[4:7]
	v_mfma_f32_16x16x32_bf16 v[0:3], v[228:231], v[212:215], v[0:3]
	s_setprio 0
	s_add_i32 s19, s19, 2
	s_add_u32 s72, s72, 0x100
	s_addc_u32 s73, s73, 0
	s_add_u32 s17, s17, 0x100
	s_addc_u32 s18, s18, 0
	s_cmp_gt_u32 s19, 13
	s_barrier
	s_cbranch_scc0 .LBB0_187
	v_lshl_add_u32 v156, s75, 8, v9
	s_lshl_b32 s1, s15, 1
	s_mul_i32 s15, s15, 0x1100000
	s_mul_hi_i32 s1, s1, 0x880000
	s_add_u32 s66, s82, s15
	v_ashrrev_i32_e32 v157, 31, v156
	s_addc_u32 s67, s83, s1
	v_lshlrev_b64 v[158:159], 8, v[156:157]
	v_lshl_add_u64 v[158:159], s[66:67], 0, v[158:159]
	v_lshl_add_u64 v[158:159], v[158:159], 0, s[2:3]
	v_mov_b32_e32 v153, v8
	v_lshl_add_u64 v[158:159], v[158:159], 0, v[152:153]
	v_cvt_pk_bf16_f32 v114, v114, v115
	v_cvt_pk_bf16_f32 v115, v116, v117
	v_cvt_pk_bf16_f32 v116, v106, v107
	v_add_co_u32_e32 v106, vcc, s87, v158
	v_cvt_pk_bf16_f32 v117, v108, v109
	s_nop 0
	v_addc_co_u32_e32 v107, vcc, 0, v159, vcc
	global_store_dwordx4 v[106:107], v[114:117], off
	v_or_b32_e32 v106, 16, v156
	v_ashrrev_i32_e32 v107, 31, v106
	v_lshlrev_b64 v[106:107], 8, v[106:107]
	v_lshl_add_u64 v[106:107], s[66:67], 0, v[106:107]
	v_lshl_add_u64 v[106:107], v[106:107], 0, s[2:3]
	v_lshl_add_u64 v[114:115], v[106:107], 0, v[152:153]
	v_cvt_pk_bf16_f32 v98, v98, v99
	v_cvt_pk_bf16_f32 v99, v100, v101
	v_cvt_pk_bf16_f32 v100, v90, v91
	v_add_co_u32_e32 v90, vcc, s87, v114
	v_cvt_pk_bf16_f32 v101, v92, v93
	s_nop 0
	v_addc_co_u32_e32 v91, vcc, 0, v115, vcc
	global_store_dwordx4 v[90:91], v[98:101], off
	v_or_b32_e32 v90, 32, v156
	v_ashrrev_i32_e32 v91, 31, v90
	v_lshlrev_b64 v[90:91], 8, v[90:91]
	v_lshl_add_u64 v[90:91], s[66:67], 0, v[90:91]
	v_lshl_add_u64 v[90:91], v[90:91], 0, s[2:3]
	v_lshl_add_u64 v[98:99], v[90:91], 0, v[152:153]
	v_cvt_pk_bf16_f32 v82, v82, v83
	v_cvt_pk_bf16_f32 v83, v84, v85
	v_cvt_pk_bf16_f32 v84, v74, v75
	v_add_co_u32_e32 v74, vcc, s87, v98
	v_cvt_pk_bf16_f32 v85, v76, v77
	s_nop 0
	v_addc_co_u32_e32 v75, vcc, 0, v99, vcc
	global_store_dwordx4 v[74:75], v[82:85], off
	v_or_b32_e32 v74, 48, v156
	v_ashrrev_i32_e32 v75, 31, v74
	v_lshlrev_b64 v[74:75], 8, v[74:75]
	v_lshl_add_u64 v[74:75], s[66:67], 0, v[74:75]
	v_lshl_add_u64 v[74:75], v[74:75], 0, s[2:3]
	v_lshl_add_u64 v[82:83], v[74:75], 0, v[152:153]
	v_cvt_pk_bf16_f32 v70, v70, v71
	v_cvt_pk_bf16_f32 v71, v72, v73
	v_cvt_pk_bf16_f32 v72, v66, v67
	v_add_co_u32_e32 v66, vcc, s87, v82
	s_mov_b32 s1, 0x9000
	s_nop 0
	v_addc_co_u32_e32 v67, vcc, 0, v83, vcc
	v_cvt_pk_bf16_f32 v62, v62, v63
	v_cvt_pk_bf16_f32 v63, v64, v65
	v_cvt_pk_bf16_f32 v64, v58, v59
	v_add_co_u32_e32 v58, vcc, s1, v158
	s_mov_b32 s1, 0x889000
	s_nop 0
	v_addc_co_u32_e32 v59, vcc, 0, v159, vcc
	v_cvt_pk_bf16_f32 v65, v60, v61
	v_add_co_u32_e32 v60, vcc, s1, v158
	v_cvt_pk_bf16_f32 v30, v30, v31
	s_nop 0
	v_addc_co_u32_e32 v61, vcc, 0, v159, vcc
	v_cvt_pk_bf16_f32 v31, v32, v33
	v_cvt_pk_bf16_f32 v32, v26, v27
	v_cvt_pk_bf16_f32 v33, v28, v29
	s_mov_b32 s1, 0xb000
	global_store_dwordx4 v[60:61], v[30:33], off
	v_cvt_pk_bf16_f32 v14, v14, v15
	v_cvt_pk_bf16_f32 v15, v16, v17
	v_add_co_u32_e32 v30, vcc, s1, v158
	s_mov_b32 s1, 0x88a000
	s_nop 0
	v_addc_co_u32_e32 v31, vcc, 0, v159, vcc
	v_cvt_pk_bf16_f32 v16, v10, v11
	v_add_co_u32_e32 v10, vcc, s1, v158
	v_cvt_pk_bf16_f32 v4, v4, v5
	s_nop 0
	v_addc_co_u32_e32 v11, vcc, 0, v159, vcc
	v_cvt_pk_bf16_f32 v5, v6, v7
	v_cvt_pk_bf16_f32 v6, v0, v1
	v_add_co_u32_e32 v0, vcc, 0x88b000, v158
	v_cvt_pk_bf16_f32 v17, v12, v13
	s_nop 0
	v_addc_co_u32_e32 v1, vcc, 0, v159, vcc
	v_cvt_pk_bf16_f32 v126, v126, v127
	v_cvt_pk_bf16_f32 v127, v128, v129
	v_cvt_pk_bf16_f32 v128, v122, v123
	v_cvt_pk_bf16_f32 v129, v124, v125
	v_cvt_pk_bf16_f32 v106, v118, v119
	v_cvt_pk_bf16_f32 v107, v120, v121
	v_cvt_pk_bf16_f32 v108, v110, v111
	v_cvt_pk_bf16_f32 v109, v112, v113
	v_cvt_pk_bf16_f32 v90, v102, v103
	v_cvt_pk_bf16_f32 v91, v104, v105
	v_cvt_pk_bf16_f32 v92, v94, v95
	v_cvt_pk_bf16_f32 v93, v96, v97
	v_cvt_pk_bf16_f32 v74, v86, v87
	v_cvt_pk_bf16_f32 v75, v88, v89
	v_cvt_pk_bf16_f32 v76, v78, v79
	v_cvt_pk_bf16_f32 v77, v80, v81
	v_cvt_pk_bf16_f32 v73, v68, v69
	v_cvt_pk_bf16_f32 v46, v46, v47
	v_cvt_pk_bf16_f32 v47, v48, v49
	v_cvt_pk_bf16_f32 v48, v42, v43
	v_cvt_pk_bf16_f32 v49, v44, v45
	v_cvt_pk_bf16_f32 v42, v54, v55
	v_cvt_pk_bf16_f32 v43, v56, v57
	v_cvt_pk_bf16_f32 v44, v50, v51
	v_cvt_pk_bf16_f32 v45, v52, v53
	v_cvt_pk_bf16_f32 v26, v38, v39
	v_cvt_pk_bf16_f32 v27, v40, v41
	v_cvt_pk_bf16_f32 v28, v34, v35
	v_cvt_pk_bf16_f32 v29, v36, v37
	global_store_dwordx4 v[10:11], v[14:17], off
	v_cvt_pk_bf16_f32 v10, v22, v23
	v_cvt_pk_bf16_f32 v11, v24, v25
	v_cvt_pk_bf16_f32 v12, v18, v19
	v_cvt_pk_bf16_f32 v13, v20, v21
	v_cvt_pk_bf16_f32 v7, v2, v3
	s_and_b64 vcc, exec, s[38:39]
	s_mov_b32 s15, s0
	s_mov_b32 s75, s40
	s_mov_b64 s[66:67], s[88:89]
	s_mov_b64 s[70:71], s[42:43]
	global_store_dwordx4 v[158:159], v[126:129], off
	global_store_dwordx4 v[114:115], v[106:109], off
	global_store_dwordx4 v[98:99], v[90:93], off
	global_store_dwordx4 v[82:83], v[74:77], off
	global_store_dwordx4 v[66:67], v[70:73], off
	global_store_dwordx4 v[58:59], v[62:65], off offset:-4096
	global_store_dwordx4 v[60:61], v[46:49], off offset:-4096
	global_store_dwordx4 v[58:59], v[42:45], off
	global_store_dwordx4 v[30:31], v[26:29], off offset:-4096
	global_store_dwordx4 v[30:31], v[10:13], off
	global_store_dwordx4 v[0:1], v[4:7], off
	s_cbranch_vccz .LBB0_184
	s_waitcnt vmcnt(0)
	v_readlane_b32 s14, v244, 49
	v_readlane_b32 s16, v244, 51
	v_readlane_b32 s70, v244, 55
	s_cmpk_gt_u32 s5, 0xff
	v_readlane_b32 s15, v244, 50
	v_readlane_b32 s17, v244, 52
	v_readlane_b32 s71, v244, 56
	s_cbranch_scc1 .LBB0_191
	s_barrier

; #define PG8_STAGE(bufoff, gbase, voff) do { _Pragma("unroll") for (int _i = 0; _i < 2; ++_i) \
;         __builtin_amdgcn_global_load_lds((const unsigned*)((const char*)(gbase) + (voff)[_i]), (LAS unsigned*)(lds + (bufoff) + ldsw + _i * 8192), 16, 0, 0); } while (0)
; #define PG8_LDA(dst, b, h) do { _Pragma("unroll") for (int m = 0; m < 4; ++m) _Pragma("unroll") for (int k = 0; k < 2; ++k) dst[m][k] = *(const LAS bf16x8*)(lds + PG8_SA(b, h) + aoff + m * 2048 + k * 1024); } while (0)
; #define PG8_LDB(dst, b, h) do { _Pragma("unroll") for (int n = 0; n < 2; ++n) _Pragma("unroll") for (int k = 0; k < 2; ++k) dst[n][k] = *(const LAS bf16x8*)(lds + PG8_SB(b, h) + boff + n * 2048 + k * 1024); } while (0)
; #define PG8_MMA(ai, bj, At, Bt) do { __builtin_amdgcn_s_setprio(1); _Pragma("unroll") for (int m = 0; m < 4; ++m) _Pragma("unroll") for (int n = 0; n < 2; ++n) _Pragma("unroll") for (int k = 0; k < 2; ++k) \
;         acc[ai][bj][m][n] = __builtin_amdgcn_mfma_f32_16x16x32_bf16(Bt[n][k], At[m][k], acc[ai][bj][m][n], 0, 0, 0); __builtin_amdgcn_s_setprio(0); } while (0)
; #define PG8_BAR __builtin_amdgcn_s_barrier()
; template <class Epi, class Sched>
; __device__ __forceinline__ void gemm_phase(LAS unsigned char* lds, const Gemm g, const Sched& S, const Epi& E) {
;     ...
;         const bool has_next = S.next(ui + 1, nxt);
;         const char* nA = has_next ? (const char*)g.A + (size_t)nxt.pm * tstep : cA; const char* nB = has_next ? (const char*)g.Bt + (size_t)nxt.pn * tstep : cB;
;         for (int t = 0; t < nt; t += 2) {
;             const bool last = (t == nt - 2);
;             const char* a1 = cA + (size_t)(t + 1) * kstep;
;             const char* a2 = last ? nA : cA + (size_t)(t + 2) * kstep; const char* b2 = last ? nB : cB + (size_t)(t + 2) * kstep;
;             const char* a3 = a2 + kstep; const char* b3 = b2 + kstep;
;             if (last && has_next) S.a_ready(nxt);
;             PG8_LDB(B0, 0, 0); PG8_SCHED; PG8_LDA(At, 0, 0); PG8_STAGE(PG8_SA(1, 1), a1 + hstep, voffA);
;             PG8_WAIT_L(8); PG8_BAR; PG8_WAIT_L(0); PG8_MMA(0, 0, At, B0); PG8_BAR; PG8_SCHED;
;     ...
;         for (int a = 0; a < 2; ++a)
; #pragma unroll
;             for (int b = 0; b < 2; ++b)
; #pragma unroll
;                 for (int m = 0; m < 4; ++m)
; #pragma unroll
;                     for (int n = 0; n < 2; ++n) acc[a][b][m][n] = (f32x4){0.f, 0.f, 0.f, 0.f};
.LBB0_514:
	s_ashr_i32 s89, s88, 31
	s_lshl_b64 s[16:17], s[88:89], 19
	v_mov_b64_e32 v[0:1], s[2:3]
	s_add_u32 s78, s76, s16
	v_cmp_lt_i64_e32 vcc, s[66:67], v[0:1]
	s_addc_u32 s79, s77, s17
	s_and_b64 s[16:17], vcc, exec
	s_cselect_b32 s89, s79, s73
	s_cselect_b32 s16, s78, s72
	s_ashr_i32 s43, s42, 31
	s_lshl_b64 s[18:19], s[42:43], 19
	s_add_u32 s70, s7, s18
	s_addc_u32 s71, s8, s19
	s_and_b64 s[18:19], vcc, exec
	s_cselect_b32 s17, s71, s75
	s_cselect_b32 s43, s70, s74
	s_add_u32 vcc_lo, s72, 0x40080
	s_addc_u32 vcc_hi, s73, 0
	s_add_u32 s74, s74, 0x100
	v_mov_b64_e32 v[82:83], 0
	v_mov_b64_e32 v[84:85], 0
	v_mov_b64_e32 v[86:87], 0
	v_mov_b64_e32 v[88:89], 0
	v_mov_b64_e32 v[98:99], 0
	v_mov_b64_e32 v[100:101], 0
	v_mov_b64_e32 v[102:103], 0
	v_mov_b64_e32 v[104:105], 0
	v_mov_b64_e32 v[114:115], 0
	v_mov_b64_e32 v[116:117], 0
	v_mov_b64_e32 v[118:119], 0
	v_mov_b64_e32 v[120:121], 0
	v_mov_b64_e32 v[122:123], 0
	v_mov_b64_e32 v[124:125], 0
	v_mov_b64_e32 v[126:127], 0
	v_mov_b64_e32 v[128:129], 0
	s_addc_u32 s18, s75, 0
	s_mov_b32 s19, -2
.LBB0_515:
	s_add_u32 s20, vcc_lo, 0xfffc0080
	s_addc_u32 s21, vcc_hi, -1
	s_add_i32 s22, 16, 0x10000
	v_add_u32_e32 v155, s22, v152
	ds_read_b128 v[156:159], v155
	ds_read_b128 v[160:163], v155 offset:1024
	ds_read_b128 v[164:167], v155 offset:2048
	ds_read_b128 v[168:171], v155 offset:3072
	s_cmp_eq_u32 s19, 12
	s_cselect_b32 s73, s89, s21
	s_cselect_b32 s72, s16, s20
	s_cselect_b32 s67, s17, s18
	s_cselect_b32 s66, s43, s74
	v_lshl_add_u64 v[216:217], vcc, 0, v[148:149]
	s_add_i32 m0, s1, 0xc000
	ds_read_b128 v[172:175], v154
	ds_read_b128 v[188:191], v154 offset:1024
	ds_read_b128 v[192:195], v154 offset:2048
	ds_read_b128 v[196:199], v154 offset:3072
	ds_read_b128 v[200:203], v154 offset:4096
	ds_read_b128 v[204:207], v154 offset:5120
	ds_read_b128 v[208:211], v154 offset:6144
	ds_read_b128 v[212:215], v154 offset:7168
	global_load_lds_dwordx4 v[216:217], off
	v_lshl_add_u64 v[216:217], vcc, 0, v[150:151]
	s_add_i32 m0, s1, 0xe000
	s_nop 0
	global_load_lds_dwordx4 v[216:217], off
	s_cmp_lg_u32 s19, -2
	s_cbranch_scc1 .Lzd512
	v_mov_b64_e32 v[66:67], 0
	v_mov_b64_e32 v[68:69], 0
	v_mov_b64_e32 v[70:71], 0
	v_mov_b64_e32 v[72:73], 0
	v_mov_b64_e32 v[74:75], 0
	v_mov_b64_e32 v[76:77], 0
	v_mov_b64_e32 v[78:79], 0
	v_mov_b64_e32 v[80:81], 0
	v_mov_b64_e32 v[90:91], 0
	v_mov_b64_e32 v[92:93], 0
	v_mov_b64_e32 v[94:95], 0
	v_mov_b64_e32 v[96:97], 0
	v_mov_b64_e32 v[106:107], 0
	v_mov_b64_e32 v[108:109], 0
	v_mov_b64_e32 v[110:111], 0
	v_mov_b64_e32 v[112:113], 0
	v_mov_b64_e32 v[18:19], 0
	v_mov_b64_e32 v[20:21], 0
	v_mov_b64_e32 v[22:23], 0
	v_mov_b64_e32 v[24:25], 0
	v_mov_b64_e32 v[34:35], 0
	v_mov_b64_e32 v[36:37], 0
	v_mov_b64_e32 v[38:39], 0
	v_mov_b64_e32 v[40:41], 0
	v_mov_b64_e32 v[50:51], 0
	v_mov_b64_e32 v[52:53], 0
	v_mov_b64_e32 v[54:55], 0
	v_mov_b64_e32 v[56:57], 0
	v_mov_b64_e32 v[58:59], 0
	v_mov_b64_e32 v[60:61], 0
	v_mov_b64_e32 v[62:63], 0
	v_mov_b64_e32 v[64:65], 0
	v_mov_b64_e32 v[0:1], 0
	v_mov_b64_e32 v[2:3], 0
	v_mov_b64_e32 v[4:5], 0
	v_mov_b64_e32 v[6:7], 0
	v_mov_b64_e32 v[10:11], 0
	v_mov_b64_e32 v[12:13], 0
	v_mov_b64_e32 v[14:15], 0
	v_mov_b64_e32 v[16:17], 0
	v_mov_b64_e32 v[26:27], 0
	v_mov_b64_e32 v[28:29], 0
	v_mov_b64_e32 v[30:31], 0
	v_mov_b64_e32 v[32:33], 0
	v_mov_b64_e32 v[42:43], 0
	v_mov_b64_e32 v[44:45], 0
	v_mov_b64_e32 v[46:47], 0
	v_mov_b64_e32 v[48:49], 0
.Lzd512:
	s_waitcnt lgkmcnt(8)
	s_barrier
	s_waitcnt lgkmcnt(0)
	s_setprio 1
	s_waitcnt lgkmcnt(0)
	v_mfma_f32_16x16x32_bf16 v[126:129], v[156:159], v[172:175], v[126:129]
	v_mfma_f32_16x16x32_bf16 v[122:125], v[164:167], v[172:175], v[122:125]
	v_mfma_f32_16x16x32_bf16 v[118:121], v[156:159], v[192:195], v[118:121]
	v_mfma_f32_16x16x32_bf16 v[114:117], v[164:167], v[192:195], v[114:117]
	v_mfma_f32_16x16x32_bf16 v[102:105], v[156:159], v[200:203], v[102:105]
	v_mfma_f32_16x16x32_bf16 v[98:101], v[164:167], v[200:203], v[98:101]
	v_mfma_f32_16x16x32_bf16 v[86:89], v[156:159], v[208:211], v[86:89]
	v_mfma_f32_16x16x32_bf16 v[82:85], v[164:167], v[208:211], v[82:85]
	v_mfma_f32_16x16x32_bf16 v[126:129], v[160:163], v[188:191], v[126:129]
	v_mfma_f32_16x16x32_bf16 v[122:125], v[168:171], v[188:191], v[122:125]
	v_mfma_f32_16x16x32_bf16 v[118:121], v[160:163], v[196:199], v[118:121]
	v_mfma_f32_16x16x32_bf16 v[114:117], v[168:171], v[196:199], v[114:117]
	v_mfma_f32_16x16x32_bf16 v[102:105], v[160:163], v[204:207], v[102:105]
	v_mfma_f32_16x16x32_bf16 v[98:101], v[168:171], v[204:207], v[98:101]
	v_mfma_f32_16x16x32_bf16 v[86:89], v[160:163], v[212:215], v[86:89]
	v_mfma_f32_16x16x32_bf16 v[82:85], v[168:171], v[212:215], v[82:85]
	s_setprio 0
	s_barrier
	s_add_i32 s23, 16, 0x14000
	s_add_i32 s20, s22, s9
	v_add_u32_e32 v155, s23, v152
	v_lshl_add_u64 v[232:233], s[66:67], 0, v[144:145]
	s_mov_b32 m0, s20
	ds_read_b128 v[216:219], v155
	ds_read_b128 v[220:223], v155 offset:1024
	ds_read_b128 v[224:227], v155 offset:2048
	ds_read_b128 v[228:231], v155 offset:3072
	global_load_lds_dwordx4 v[232:233], off
	v_lshl_add_u64 v[234:235], s[66:67], 0, v[140:141]
	s_add_i32 m0, s20, 0x2000
	s_nop 0
	global_load_lds_dwordx4 v[234:235], off
	s_barrier
; #define PG8_STAGE(bufoff, gbase, voff) do { _Pragma("unroll") for (int _i = 0; _i < 2; ++_i) \
;         __builtin_amdgcn_global_load_lds((const unsigned*)((const char*)(gbase) + (voff)[_i]), (LAS unsigned*)(lds + (bufoff) + ldsw + _i * 8192), 16, 0, 0); } while (0)
; #define PG8_LDA(dst, b, h) do { _Pragma("unroll") for (int m = 0; m < 4; ++m) _Pragma("unroll") for (int k = 0; k < 2; ++k) dst[m][k] = *(const LAS bf16x8*)(lds + PG8_SA(b, h) + aoff + m * 2048 + k * 1024); } while (0)
; #define PG8_LDB(dst, b, h) do { _Pragma("unroll") for (int n = 0; n < 2; ++n) _Pragma("unroll") for (int k = 0; k < 2; ++k) dst[n][k] = *(const LAS bf16x8*)(lds + PG8_SB(b, h) + boff + n * 2048 + k * 1024); } while (0)
; #define PG8_MMA(ai, bj, At, Bt) do { __builtin_amdgcn_s_setprio(1); _Pragma("unroll") for (int m = 0; m < 4; ++m) _Pragma("unroll") for (int n = 0; n < 2; ++n) _Pragma("unroll") for (int k = 0; k < 2; ++k) \
;         acc[ai][bj][m][n] = __builtin_amdgcn_mfma_f32_16x16x32_bf16(Bt[n][k], At[m][k], acc[ai][bj][m][n], 0, 0, 0); __builtin_amdgcn_s_setprio(0); } while (0)
; #define PG8_WAIT_V(n) asm volatile("s_waitcnt vmcnt(" #n ")" ::: "memory")
; #define PG8_WAIT_L(n) asm volatile("s_waitcnt lgkmcnt(" #n ")" ::: "memory")
; #define PG8_BAR __builtin_amdgcn_s_barrier()
; #define PG8_SCHED __builtin_amdgcn_sched_barrier(0)
; template <class Epi, class Sched>
; __device__ __forceinline__ void gemm_phase(LAS unsigned char* lds, const Gemm g, const Sched& S, const Epi& E) {
;     ...
;             PG8_BAR; PG8_WAIT_L(0); PG8_MMA(0, 1, At, B1); PG8_BAR;
;             PG8_LDA(At, 0, 1); PG8_STAGE(PG8_SA(0, 0), a2, voffA);
;             PG8_BAR; PG8_WAIT_L(0); PG8_MMA(1, 0, At, B0); PG8_BAR; PG8_SCHED;
;             PG8_STAGE(PG8_SB(0, 1), b2 + hstep, voffB);
;             PG8_WAIT_V(6); PG8_BAR; PG8_MMA(1, 1, At, B1); PG8_BAR;
;             PG8_LDB(B0, 1, 0); PG8_SCHED; PG8_LDA(At, 1, 0); PG8_STAGE(PG8_SA(0, 1), a2 + hstep, voffA);
;             PG8_WAIT_L(8); PG8_BAR; PG8_WAIT_L(0); PG8_MMA(0, 0, At, B0); PG8_BAR; PG8_SCHED;
	s_waitcnt lgkmcnt(0)
	s_setprio 1
	s_waitcnt lgkmcnt(0)
	v_mfma_f32_16x16x32_bf16 v[110:113], v[216:219], v[172:175], v[110:113]
	v_mfma_f32_16x16x32_bf16 v[106:109], v[224:227], v[172:175], v[106:109]
	v_mfma_f32_16x16x32_bf16 v[94:97], v[216:219], v[192:195], v[94:97]
	v_mfma_f32_16x16x32_bf16 v[90:93], v[224:227], v[192:195], v[90:93]
	v_mfma_f32_16x16x32_bf16 v[78:81], v[216:219], v[200:203], v[78:81]
	v_mfma_f32_16x16x32_bf16 v[74:77], v[224:227], v[200:203], v[74:77]
	v_mfma_f32_16x16x32_bf16 v[70:73], v[216:219], v[208:211], v[70:73]
	v_mfma_f32_16x16x32_bf16 v[66:69], v[224:227], v[208:211], v[66:69]
	v_mfma_f32_16x16x32_bf16 v[110:113], v[220:223], v[188:191], v[110:113]
	v_mfma_f32_16x16x32_bf16 v[106:109], v[228:231], v[188:191], v[106:109]
	v_mfma_f32_16x16x32_bf16 v[94:97], v[220:223], v[196:199], v[94:97]
	v_mfma_f32_16x16x32_bf16 v[90:93], v[228:231], v[196:199], v[90:93]
	v_mfma_f32_16x16x32_bf16 v[78:81], v[220:223], v[204:207], v[78:81]
	v_mfma_f32_16x16x32_bf16 v[74:77], v[228:231], v[204:207], v[74:77]
	v_mfma_f32_16x16x32_bf16 v[70:73], v[220:223], v[212:215], v[70:73]
	v_mfma_f32_16x16x32_bf16 v[66:69], v[228:231], v[212:215], v[66:69]
	s_setprio 0
	s_mov_b32 m0, s1
	v_lshl_add_u64 v[236:237], s[72:73], 0, v[146:147]
	s_barrier
	ds_read_b128 v[172:175], v154 offset:16384
	ds_read_b128 v[188:191], v154 offset:17408
	ds_read_b128 v[192:195], v154 offset:18432
	ds_read_b128 v[196:199], v154 offset:19456
	ds_read_b128 v[200:203], v154 offset:20480
	ds_read_b128 v[204:207], v154 offset:21504
	ds_read_b128 v[208:211], v154 offset:22528
	ds_read_b128 v[212:215], v154 offset:23552
	global_load_lds_dwordx4 v[236:237], off
	v_lshl_add_u64 v[238:239], s[72:73], 0, v[142:143]
	s_mov_b32 m0, s11
	s_nop 0
	global_load_lds_dwordx4 v[238:239], off
	s_barrier
	s_waitcnt lgkmcnt(0)
	s_setprio 1
	s_waitcnt lgkmcnt(0)
	v_mfma_f32_16x16x32_bf16 v[62:65], v[156:159], v[172:175], v[62:65]
	v_mfma_f32_16x16x32_bf16 v[58:61], v[164:167], v[172:175], v[58:61]
	v_mfma_f32_16x16x32_bf16 v[54:57], v[156:159], v[192:195], v[54:57]
	v_mfma_f32_16x16x32_bf16 v[50:53], v[164:167], v[192:195], v[50:53]
	v_mfma_f32_16x16x32_bf16 v[38:41], v[156:159], v[200:203], v[38:41]
	v_mfma_f32_16x16x32_bf16 v[34:37], v[164:167], v[200:203], v[34:37]
	v_mfma_f32_16x16x32_bf16 v[22:25], v[156:159], v[208:211], v[22:25]
	v_mfma_f32_16x16x32_bf16 v[18:21], v[164:167], v[208:211], v[18:21]
	v_mfma_f32_16x16x32_bf16 v[62:65], v[160:163], v[188:191], v[62:65]
	v_mfma_f32_16x16x32_bf16 v[58:61], v[168:171], v[188:191], v[58:61]
	v_mfma_f32_16x16x32_bf16 v[54:57], v[160:163], v[196:199], v[54:57]
	v_mfma_f32_16x16x32_bf16 v[50:53], v[168:171], v[196:199], v[50:53]
	v_mfma_f32_16x16x32_bf16 v[38:41], v[160:163], v[204:207], v[38:41]
	v_mfma_f32_16x16x32_bf16 v[34:37], v[168:171], v[204:207], v[34:37]
	v_mfma_f32_16x16x32_bf16 v[22:25], v[160:163], v[212:215], v[22:25]
	v_mfma_f32_16x16x32_bf16 v[18:21], v[168:171], v[212:215], v[18:21]
	s_setprio 0
	s_barrier
	s_add_u32 s20, s66, 0x40000
	s_addc_u32 s21, s67, 0
	s_add_i32 s22, s23, s9
	v_lshl_add_u64 v[156:157], s[20:21], 0, v[144:145]
	s_mov_b32 m0, s22
	s_nop 0
	global_load_lds_dwordx4 v[156:157], off
	v_lshl_add_u64 v[156:157], s[20:21], 0, v[140:141]
	s_add_i32 m0, s22, 0x2000
	s_nop 0
	global_load_lds_dwordx4 v[156:157], off
	s_waitcnt vmcnt(6)
	s_barrier
	s_setprio 1
	v_mfma_f32_16x16x32_bf16 v[46:49], v[216:219], v[172:175], v[46:49]
	v_mfma_f32_16x16x32_bf16 v[42:45], v[224:227], v[172:175], v[42:45]
	v_mfma_f32_16x16x32_bf16 v[30:33], v[216:219], v[192:195], v[30:33]
	v_mfma_f32_16x16x32_bf16 v[26:29], v[224:227], v[192:195], v[26:29]
	v_mfma_f32_16x16x32_bf16 v[14:17], v[216:219], v[200:203], v[14:17]
	v_mfma_f32_16x16x32_bf16 v[10:13], v[224:227], v[200:203], v[10:13]
	v_mfma_f32_16x16x32_bf16 v[4:7], v[216:219], v[208:211], v[4:7]
	v_mfma_f32_16x16x32_bf16 v[0:3], v[224:227], v[208:211], v[0:3]
	v_mfma_f32_16x16x32_bf16 v[46:49], v[220:223], v[188:191], v[46:49]
	v_mfma_f32_16x16x32_bf16 v[42:45], v[228:231], v[188:191], v[42:45]
	v_mfma_f32_16x16x32_bf16 v[30:33], v[220:223], v[196:199], v[30:33]
	v_mfma_f32_16x16x32_bf16 v[26:29], v[228:231], v[196:199], v[26:29]
	v_mfma_f32_16x16x32_bf16 v[14:17], v[220:223], v[204:207], v[14:17]
	v_mfma_f32_16x16x32_bf16 v[10:13], v[228:231], v[204:207], v[10:13]
	v_mfma_f32_16x16x32_bf16 v[4:7], v[220:223], v[212:215], v[4:7]
	v_mfma_f32_16x16x32_bf16 v[0:3], v[228:231], v[212:215], v[0:3]
	s_setprio 0
	s_add_i32 s22, 16, 0x18000
	v_add_u32_e32 v155, s22, v152
	s_barrier
	ds_read_b128 v[156:159], v155
	ds_read_b128 v[160:163], v155 offset:1024
	ds_read_b128 v[164:167], v155 offset:2048
	ds_read_b128 v[168:171], v155 offset:3072
	s_add_u32 s20, s72, 0x40000
	s_addc_u32 s21, s73, 0
	s_mov_b32 m0, s41
	v_lshl_add_u64 v[216:217], s[20:21], 0, v[146:147]
	ds_read_b128 v[172:175], v154 offset:32768
	ds_read_b128 v[188:191], v154 offset:33792
	ds_read_b128 v[192:195], v154 offset:34816
	ds_read_b128 v[196:199], v154 offset:35840
	ds_read_b128 v[200:203], v154 offset:36864
	ds_read_b128 v[204:207], v154 offset:37888
	ds_read_b128 v[208:211], v154 offset:38912
	ds_read_b128 v[212:215], v154 offset:39936
	global_load_lds_dwordx4 v[216:217], off
	v_lshl_add_u64 v[216:217], s[20:21], 0, v[142:143]
	s_mov_b32 m0, s12
	s_nop 0
	global_load_lds_dwordx4 v[216:217], off
	s_waitcnt lgkmcnt(8)
	s_barrier
; #define PG8_STAGE(bufoff, gbase, voff) do { _Pragma("unroll") for (int _i = 0; _i < 2; ++_i) \
;         __builtin_amdgcn_global_load_lds((const unsigned*)((const char*)(gbase) + (voff)[_i]), (LAS unsigned*)(lds + (bufoff) + ldsw + _i * 8192), 16, 0, 0); } while (0)
; #define PG8_LDA(dst, b, h) do { _Pragma("unroll") for (int m = 0; m < 4; ++m) _Pragma("unroll") for (int k = 0; k < 2; ++k) dst[m][k] = *(const LAS bf16x8*)(lds + PG8_SA(b, h) + aoff + m * 2048 + k * 1024); } while (0)
; #define PG8_LDB(dst, b, h) do { _Pragma("unroll") for (int n = 0; n < 2; ++n) _Pragma("unroll") for (int k = 0; k < 2; ++k) dst[n][k] = *(const LAS bf16x8*)(lds + PG8_SB(b, h) + boff + n * 2048 + k * 1024); } while (0)
; #define PG8_MMA(ai, bj, At, Bt) do { __builtin_amdgcn_s_setprio(1); _Pragma("unroll") for (int m = 0; m < 4; ++m) _Pragma("unroll") for (int n = 0; n < 2; ++n) _Pragma("unroll") for (int k = 0; k < 2; ++k) \
;         acc[ai][bj][m][n] = __builtin_amdgcn_mfma_f32_16x16x32_bf16(Bt[n][k], At[m][k], acc[ai][bj][m][n], 0, 0, 0); __builtin_amdgcn_s_setprio(0); } while (0)
; #define PG8_WAIT_V(n) asm volatile("s_waitcnt vmcnt(" #n ")" ::: "memory")
; #define PG8_WAIT_L(n) asm volatile("s_waitcnt lgkmcnt(" #n ")" ::: "memory")
; #define PG8_BAR __builtin_amdgcn_s_barrier()
; #define PG8_SCHED __builtin_amdgcn_sched_barrier(0)
; template <class Epi, class Sched>
; __device__ __forceinline__ void gemm_phase(LAS unsigned char* lds, const Gemm g, const Sched& S, const Epi& E) {
;     ...
;             PG8_WAIT_L(8); PG8_BAR; PG8_WAIT_L(0); PG8_MMA(0, 0, At, B0); PG8_BAR; PG8_SCHED;
;             PG8_LDB(B1, 1, 1); PG8_STAGE(PG8_SB(1, 0), b3, voffB);
;             PG8_BAR; PG8_WAIT_L(0); PG8_MMA(0, 1, At, B1); PG8_BAR;
;             PG8_LDA(At, 1, 1); PG8_STAGE(PG8_SA(1, 0), a3, voffA);
;             PG8_BAR; PG8_WAIT_L(0); PG8_MMA(1, 0, At, B0); PG8_BAR; PG8_SCHED;
;             PG8_STAGE(PG8_SB(1, 1), b3 + hstep, voffB);
;             PG8_WAIT_V(6); PG8_BAR; PG8_MMA(1, 1, At, B1); PG8_BAR;
	s_waitcnt lgkmcnt(0)
	s_setprio 1
	s_waitcnt lgkmcnt(0)
	v_mfma_f32_16x16x32_bf16 v[126:129], v[156:159], v[172:175], v[126:129]
	v_mfma_f32_16x16x32_bf16 v[122:125], v[164:167], v[172:175], v[122:125]
	v_mfma_f32_16x16x32_bf16 v[118:121], v[156:159], v[192:195], v[118:121]
	v_mfma_f32_16x16x32_bf16 v[114:117], v[164:167], v[192:195], v[114:117]
	v_mfma_f32_16x16x32_bf16 v[102:105], v[156:159], v[200:203], v[102:105]
	v_mfma_f32_16x16x32_bf16 v[98:101], v[164:167], v[200:203], v[98:101]
	v_mfma_f32_16x16x32_bf16 v[86:89], v[156:159], v[208:211], v[86:89]
	v_mfma_f32_16x16x32_bf16 v[82:85], v[164:167], v[208:211], v[82:85]
	v_mfma_f32_16x16x32_bf16 v[126:129], v[160:163], v[188:191], v[126:129]
	v_mfma_f32_16x16x32_bf16 v[122:125], v[168:171], v[188:191], v[122:125]
	v_mfma_f32_16x16x32_bf16 v[118:121], v[160:163], v[196:199], v[118:121]
	v_mfma_f32_16x16x32_bf16 v[114:117], v[168:171], v[196:199], v[114:117]
	v_mfma_f32_16x16x32_bf16 v[102:105], v[160:163], v[204:207], v[102:105]
	v_mfma_f32_16x16x32_bf16 v[98:101], v[168:171], v[204:207], v[98:101]
	v_mfma_f32_16x16x32_bf16 v[86:89], v[160:163], v[212:215], v[86:89]
	v_mfma_f32_16x16x32_bf16 v[82:85], v[168:171], v[212:215], v[82:85]
	s_setprio 0
	s_barrier
	s_add_i32 s23, 16, 0x1c000
	s_add_i32 s20, s22, s9
	v_add_u32_e32 v155, s23, v152
	v_lshl_add_u64 v[232:233], v[232:233], 0, s[94:95]
	s_mov_b32 m0, s20
	ds_read_b128 v[216:219], v155
	ds_read_b128 v[220:223], v155 offset:1024
	ds_read_b128 v[224:227], v155 offset:2048
	ds_read_b128 v[228:231], v155 offset:3072
	global_load_lds_dwordx4 v[232:233], off
	v_lshl_add_u64 v[232:233], v[234:235], 0, s[94:95]
	s_add_i32 m0, s20, 0x2000
	s_nop 0
	global_load_lds_dwordx4 v[232:233], off
	s_barrier
	s_waitcnt lgkmcnt(0)
	s_setprio 1
	s_waitcnt lgkmcnt(0)
	v_mfma_f32_16x16x32_bf16 v[110:113], v[216:219], v[172:175], v[110:113]
	v_mfma_f32_16x16x32_bf16 v[106:109], v[224:227], v[172:175], v[106:109]
	v_mfma_f32_16x16x32_bf16 v[94:97], v[216:219], v[192:195], v[94:97]
	v_mfma_f32_16x16x32_bf16 v[90:93], v[224:227], v[192:195], v[90:93]
	v_mfma_f32_16x16x32_bf16 v[78:81], v[216:219], v[200:203], v[78:81]
	v_mfma_f32_16x16x32_bf16 v[74:77], v[224:227], v[200:203], v[74:77]
	v_mfma_f32_16x16x32_bf16 v[70:73], v[216:219], v[208:211], v[70:73]
	v_mfma_f32_16x16x32_bf16 v[66:69], v[224:227], v[208:211], v[66:69]
	v_mfma_f32_16x16x32_bf16 v[110:113], v[220:223], v[188:191], v[110:113]
	v_mfma_f32_16x16x32_bf16 v[106:109], v[228:231], v[188:191], v[106:109]
	v_mfma_f32_16x16x32_bf16 v[94:97], v[220:223], v[196:199], v[94:97]
	v_mfma_f32_16x16x32_bf16 v[90:93], v[228:231], v[196:199], v[90:93]
	v_mfma_f32_16x16x32_bf16 v[78:81], v[220:223], v[204:207], v[78:81]
	v_mfma_f32_16x16x32_bf16 v[74:77], v[228:231], v[204:207], v[74:77]
	v_mfma_f32_16x16x32_bf16 v[70:73], v[220:223], v[212:215], v[70:73]
	v_mfma_f32_16x16x32_bf16 v[66:69], v[228:231], v[212:215], v[66:69]
	s_setprio 0
	s_mov_b32 m0, s13
	v_lshl_add_u64 v[232:233], v[236:237], 0, s[94:95]
	s_barrier
	ds_read_b128 v[172:175], v154 offset:49152
	ds_read_b128 v[188:191], v154 offset:50176
	ds_read_b128 v[192:195], v154 offset:51200
	ds_read_b128 v[196:199], v154 offset:52224
	ds_read_b128 v[200:203], v154 offset:53248
	ds_read_b128 v[204:207], v154 offset:54272
	ds_read_b128 v[208:211], v154 offset:55296
	ds_read_b128 v[212:215], v154 offset:56320
	global_load_lds_dwordx4 v[232:233], off
	v_lshl_add_u64 v[232:233], v[238:239], 0, s[94:95]
	s_mov_b32 m0, s14
	s_nop 0
	global_load_lds_dwordx4 v[232:233], off
	s_barrier
	s_waitcnt lgkmcnt(0)
	s_setprio 1
	s_waitcnt lgkmcnt(0)
	v_mfma_f32_16x16x32_bf16 v[62:65], v[156:159], v[172:175], v[62:65]
	v_mfma_f32_16x16x32_bf16 v[58:61], v[164:167], v[172:175], v[58:61]
	v_mfma_f32_16x16x32_bf16 v[54:57], v[156:159], v[192:195], v[54:57]
	v_mfma_f32_16x16x32_bf16 v[50:53], v[164:167], v[192:195], v[50:53]
	v_mfma_f32_16x16x32_bf16 v[38:41], v[156:159], v[200:203], v[38:41]
	v_mfma_f32_16x16x32_bf16 v[34:37], v[164:167], v[200:203], v[34:37]
	v_mfma_f32_16x16x32_bf16 v[22:25], v[156:159], v[208:211], v[22:25]
	v_mfma_f32_16x16x32_bf16 v[18:21], v[164:167], v[208:211], v[18:21]
	v_mfma_f32_16x16x32_bf16 v[62:65], v[160:163], v[188:191], v[62:65]
	v_mfma_f32_16x16x32_bf16 v[58:61], v[168:171], v[188:191], v[58:61]
	v_mfma_f32_16x16x32_bf16 v[54:57], v[160:163], v[196:199], v[54:57]
	v_mfma_f32_16x16x32_bf16 v[50:53], v[168:171], v[196:199], v[50:53]
	v_mfma_f32_16x16x32_bf16 v[38:41], v[160:163], v[204:207], v[38:41]
	v_mfma_f32_16x16x32_bf16 v[34:37], v[168:171], v[204:207], v[34:37]
	v_mfma_f32_16x16x32_bf16 v[22:25], v[160:163], v[212:215], v[22:25]
	v_mfma_f32_16x16x32_bf16 v[18:21], v[168:171], v[212:215], v[18:21]
	s_setprio 0
	s_barrier
	s_add_u32 s20, s66, 0x40080
	s_addc_u32 s21, s67, 0
	s_add_i32 s22, s23, s9
	v_lshl_add_u64 v[156:157], s[20:21], 0, v[144:145]
	s_mov_b32 m0, s22
	s_nop 0
	global_load_lds_dwordx4 v[156:157], off
	v_lshl_add_u64 v[156:157], s[20:21], 0, v[140:141]
	s_add_i32 m0, s22, 0x2000
	s_nop 0
	global_load_lds_dwordx4 v[156:157], off
	s_waitcnt vmcnt(6)
	s_barrier
; __device__ __forceinline__ unsigned pk_bf16(float a, float b) { f32x2 v = {a, b}; bf2_t r = __builtin_convertvector(v, bf2_t); return __builtin_bit_cast(unsigned, r); }
; #define PG8_MMA(ai, bj, At, Bt) do { __builtin_amdgcn_s_setprio(1); _Pragma("unroll") for (int m = 0; m < 4; ++m) _Pragma("unroll") for (int n = 0; n < 2; ++n) _Pragma("unroll") for (int k = 0; k < 2; ++k) \
;         acc[ai][bj][m][n] = __builtin_amdgcn_mfma_f32_16x16x32_bf16(Bt[n][k], At[m][k], acc[ai][bj][m][n], 0, 0, 0); __builtin_amdgcn_s_setprio(0); } while (0)
; #define PG8_WAIT_V(n) asm volatile("s_waitcnt vmcnt(" #n ")" ::: "memory")
;     __device__ __forceinline__ void operator()(const f32x4 (&acc)[2][2][4][2], const Unit& u, int wr, int wc, int fr, int fq) const {
;         const int row0 = u.pm * BM + wr * 64 + fr; int colt = u.pn * BM; bf16_t* base = O;
;         if (split_cols) { const int t = colt / split_cols; base += (size_t)t * split_stride; colt -= t * split_cols; }
;         const int col0 = colt + wc * 32 + 8 * fq;
; #pragma unroll
;         for (int ai = 0; ai < 2; ++ai)
; #pragma unroll
;             for (int m = 0; m < 4; ++m) { const int row = row0 + ai * HALF + m * 16;
;                 bf16_t* rowp = slot_stride ? base + (size_t)(colt >> 7) * slot_stride + (size_t)row * 128 + wc * 32 + 8 * fq : base + (size_t)row * ldc + col0;
; #pragma unroll
;                 for (int bj = 0; bj < 2; ++bj) { const f32x4 v0 = acc[ai][bj][m][0], v1 = acc[ai][bj][m][1];
;                     u32x4 w; w.x = pk_bf16(v0[0], v0[1]); w.y = pk_bf16(v0[2], v0[3]); w.z = pk_bf16(v1[0], v1[1]); w.w = pk_bf16(v1[2], v1[3]);
;                     *(u32x4*)(rowp + (slot_stride ? (size_t)bj * slot_stride : (size_t)bj * HALF)) = w; } }
; template <class Epi, class Sched>
; __device__ __forceinline__ void gemm_phase(LAS unsigned char* lds, const Gemm g, const Sched& S, const Epi& E) {
;     ...
;             PG8_WAIT_V(6); PG8_BAR; PG8_MMA(1, 1, At, B1); PG8_BAR;
;         }
;         E(acc, cur, wr, wc, fr, fq); S.done(cur);
;         if (!has_next) break;
; #pragma unroll
;         for (int a = 0; a < 2; ++a)
; #pragma unroll
;             for (int b = 0; b < 2; ++b)
; #pragma unroll
;                 for (int m = 0; m < 4; ++m)
; #pragma unroll
;                     for (int n = 0; n < 2; ++n) acc[a][b][m][n] = (f32x4){0.f, 0.f, 0.f, 0.f};
;         cur = nxt; cA = nA; cB = nB; ++ui;
;     }
	s_setprio 1
	v_mfma_f32_16x16x32_bf16 v[46:49], v[216:219], v[172:175], v[46:49]
	v_mfma_f32_16x16x32_bf16 v[42:45], v[224:227], v[172:175], v[42:45]
	v_mfma_f32_16x16x32_bf16 v[30:33], v[216:219], v[192:195], v[30:33]
	v_mfma_f32_16x16x32_bf16 v[26:29], v[224:227], v[192:195], v[26:29]
	v_mfma_f32_16x16x32_bf16 v[14:17], v[216:219], v[200:203], v[14:17]
	v_mfma_f32_16x16x32_bf16 v[10:13], v[224:227], v[200:203], v[10:13]
	v_mfma_f32_16x16x32_bf16 v[4:7], v[216:219], v[208:211], v[4:7]
	v_mfma_f32_16x16x32_bf16 v[0:3], v[224:227], v[208:211], v[0:3]
	v_mfma_f32_16x16x32_bf16 v[46:49], v[220:223], v[188:191], v[46:49]
	v_mfma_f32_16x16x32_bf16 v[42:45], v[228:231], v[188:191], v[42:45]
	v_mfma_f32_16x16x32_bf16 v[30:33], v[220:223], v[196:199], v[30:33]
	v_mfma_f32_16x16x32_bf16 v[26:29], v[228:231], v[196:199], v[26:29]
	v_mfma_f32_16x16x32_bf16 v[14:17], v[220:223], v[204:207], v[14:17]
	v_mfma_f32_16x16x32_bf16 v[10:13], v[228:231], v[204:207], v[10:13]
	v_mfma_f32_16x16x32_bf16 v[4:7], v[220:223], v[212:215], v[4:7]
	v_mfma_f32_16x16x32_bf16 v[0:3], v[228:231], v[212:215], v[0:3]
	s_setprio 0
	s_add_i32 s19, s19, 2
	s_add_u32 vcc_lo, vcc_lo, 0x100
	s_addc_u32 vcc_hi, vcc_hi, 0
	s_add_u32 s74, s74, 0x100
	s_addc_u32 s18, s18, 0
	s_cmp_gt_u32 s19, 13
	s_barrier
	s_cbranch_scc0 .LBB0_515
	v_lshl_add_u32 v156, s40, 8, v9
	v_lshl_or_b32 v158, s0, 8, v153
	v_ashrrev_i32_e32 v159, 31, v158
	v_ashrrev_i32_e32 v157, 31, v156
	v_lshl_add_u64 v[158:159], v[158:159], 1, s[82:83]
	v_lshlrev_b64 v[160:161], 11, v[156:157]
	v_lshl_add_u64 v[160:161], v[158:159], 0, v[160:161]
	s_mov_b32 s0, 0x40000
	s_mov_b64 s[16:17], 0x40000
	v_cvt_pk_bf16_f32 v62, v62, v63
	v_cvt_pk_bf16_f32 v63, v64, v65
	v_cvt_pk_bf16_f32 v64, v58, v59
	v_add_co_u32_e32 v58, vcc, s0, v160
	v_cvt_pk_bf16_f32 v70, v70, v71
	v_cvt_pk_bf16_f32 v71, v72, v73
	v_cvt_pk_bf16_f32 v72, v66, v67
	v_lshl_add_u64 v[66:67], v[160:161], 0, s[16:17]
	v_addc_co_u32_e32 v59, vcc, 0, v161, vcc
	v_cvt_pk_bf16_f32 v46, v46, v47
	v_cvt_pk_bf16_f32 v47, v48, v49
	v_cvt_pk_bf16_f32 v48, v42, v43
	v_cvt_pk_bf16_f32 v49, v44, v45
	s_mov_b32 s0, 0x48000
	global_store_dwordx4 v[66:67], v[46:49], off offset:256
	s_mov_b64 s[16:17], 0x48000
	v_cvt_pk_bf16_f32 v110, v110, v111
	v_add_co_u32_e32 v48, vcc, s0, v160
	v_cvt_pk_bf16_f32 v111, v112, v113
	v_cvt_pk_bf16_f32 v112, v106, v107
	v_or_b32_e32 v106, 16, v156
	v_lshl_add_u64 v[46:47], v[160:161], 0, s[16:17]
	v_addc_co_u32_e32 v49, vcc, 0, v161, vcc
	v_cvt_pk_bf16_f32 v30, v30, v31
	v_cvt_pk_bf16_f32 v31, v32, v33
	v_cvt_pk_bf16_f32 v32, v26, v27
	v_cvt_pk_bf16_f32 v33, v28, v29
	s_mov_b32 s0, 0x50000
	v_ashrrev_i32_e32 v107, 31, v106
	v_cvt_pk_bf16_f32 v94, v94, v95
	v_cvt_pk_bf16_f32 v95, v96, v97
	v_cvt_pk_bf16_f32 v96, v90, v91
	v_or_b32_e32 v90, 32, v156
	global_store_dwordx4 v[46:47], v[30:33], off offset:256
	s_mov_b64 s[16:17], 0x50000
	v_cvt_pk_bf16_f32 v113, v108, v109
	v_add_co_u32_e32 v32, vcc, s0, v160
	v_lshlrev_b64 v[106:107], 11, v[106:107]
	v_ashrrev_i32_e32 v91, 31, v90
	v_cvt_pk_bf16_f32 v78, v78, v79
	v_cvt_pk_bf16_f32 v79, v80, v81
	v_cvt_pk_bf16_f32 v80, v74, v75
	v_or_b32_e32 v74, 48, v156
	v_lshl_add_u64 v[30:31], v[160:161], 0, s[16:17]
	v_addc_co_u32_e32 v33, vcc, 0, v161, vcc
	v_cvt_pk_bf16_f32 v14, v14, v15
	v_cvt_pk_bf16_f32 v15, v16, v17
	v_cvt_pk_bf16_f32 v16, v10, v11
	v_cvt_pk_bf16_f32 v17, v12, v13
	s_mov_b32 s0, 0x58000
	global_store_dwordx4 v[160:161], v[110:113], off offset:256
	v_cvt_pk_bf16_f32 v97, v92, v93
	v_lshlrev_b64 v[90:91], 11, v[90:91]
	v_lshl_add_u64 v[110:111], v[158:159], 0, v[106:107]
	v_ashrrev_i32_e32 v75, 31, v74
	global_store_dwordx4 v[30:31], v[14:17], off offset:256
	global_store_dwordx4 v[110:111], v[94:97], off offset:256
	v_cvt_pk_bf16_f32 v81, v76, v77
	v_add_co_u32_e32 v16, vcc, s0, v160
	v_lshl_add_u64 v[94:95], v[158:159], 0, v[90:91]
	v_lshlrev_b64 v[74:75], 11, v[74:75]
	s_mov_b64 s[16:17], 0x58000
	v_addc_co_u32_e32 v17, vcc, 0, v161, vcc
	v_cvt_pk_bf16_f32 v126, v126, v127
	v_cvt_pk_bf16_f32 v127, v128, v129
	v_cvt_pk_bf16_f32 v128, v122, v123
	v_cvt_pk_bf16_f32 v129, v124, v125
	v_cvt_pk_bf16_f32 v106, v118, v119
	v_cvt_pk_bf16_f32 v107, v120, v121
	v_cvt_pk_bf16_f32 v108, v114, v115
	v_cvt_pk_bf16_f32 v109, v116, v117
	v_cvt_pk_bf16_f32 v90, v102, v103
	v_cvt_pk_bf16_f32 v91, v104, v105
	v_cvt_pk_bf16_f32 v92, v98, v99
	v_cvt_pk_bf16_f32 v93, v100, v101
	global_store_dwordx4 v[94:95], v[78:81], off offset:256
	v_cvt_pk_bf16_f32 v76, v82, v83
	v_cvt_pk_bf16_f32 v77, v84, v85
	v_lshl_add_u64 v[78:79], v[158:159], 0, v[74:75]
	v_cvt_pk_bf16_f32 v74, v86, v87
	v_cvt_pk_bf16_f32 v75, v88, v89
	v_cvt_pk_bf16_f32 v73, v68, v69
	v_cvt_pk_bf16_f32 v65, v60, v61
	v_cvt_pk_bf16_f32 v42, v54, v55
	v_cvt_pk_bf16_f32 v43, v56, v57
	v_cvt_pk_bf16_f32 v44, v50, v51
	v_cvt_pk_bf16_f32 v45, v52, v53
	v_cvt_pk_bf16_f32 v26, v38, v39
	v_cvt_pk_bf16_f32 v27, v40, v41
	v_cvt_pk_bf16_f32 v28, v34, v35
	v_cvt_pk_bf16_f32 v29, v36, v37
	v_lshl_add_u64 v[14:15], v[160:161], 0, s[16:17]
	v_cvt_pk_bf16_f32 v10, v22, v23
	v_cvt_pk_bf16_f32 v11, v24, v25
	v_cvt_pk_bf16_f32 v12, v18, v19
	v_cvt_pk_bf16_f32 v13, v20, v21
	v_cvt_pk_bf16_f32 v4, v4, v5
	v_cvt_pk_bf16_f32 v5, v6, v7
	v_cvt_pk_bf16_f32 v6, v0, v1
	v_cvt_pk_bf16_f32 v7, v2, v3
	s_and_b64 vcc, exec, s[38:39]
	s_mov_b32 s0, s42
	s_mov_b32 s40, s88
	s_mov_b64 s[74:75], s[70:71]
	s_mov_b64 s[72:73], s[78:79]
	global_store_dwordx4 v[160:161], v[126:129], off
	global_store_dwordx4 v[110:111], v[106:109], off
	global_store_dwordx4 v[94:95], v[90:93], off
	global_store_dwordx4 v[78:79], v[74:77], off
	global_store_dwordx4 v[78:79], v[70:73], off offset:256
	global_store_dwordx4 v[58:59], v[62:65], off
	global_store_dwordx4 v[48:49], v[42:45], off
	global_store_dwordx4 v[32:33], v[26:29], off
	global_store_dwordx4 v[16:17], v[10:13], off
	global_store_dwordx4 v[14:15], v[4:7], off offset:256
	s_cbranch_vccz .LBB0_512
	s_waitcnt vmcnt(0)
	s_cmpk_gt_u32 s6, 0xff
	s_cbranch_scc1 .LBB0_519
	s_barrier

; #define PG8_STAGE(bufoff, gbase, voff) do { _Pragma("unroll") for (int _i = 0; _i < 2; ++_i) \
;         __builtin_amdgcn_global_load_lds((const unsigned*)((const char*)(gbase) + (voff)[_i]), (LAS unsigned*)(lds + (bufoff) + ldsw + _i * 8192), 16, 0, 0); } while (0)
; #define PG8_LDA(dst, b, h) do { _Pragma("unroll") for (int m = 0; m < 4; ++m) _Pragma("unroll") for (int k = 0; k < 2; ++k) dst[m][k] = *(const LAS bf16x8*)(lds + PG8_SA(b, h) + aoff + m * 2048 + k * 1024); } while (0)
; #define PG8_LDB(dst, b, h) do { _Pragma("unroll") for (int n = 0; n < 2; ++n) _Pragma("unroll") for (int k = 0; k < 2; ++k) dst[n][k] = *(const LAS bf16x8*)(lds + PG8_SB(b, h) + boff + n * 2048 + k * 1024); } while (0)
; #define PG8_MMA(ai, bj, At, Bt) do { __builtin_amdgcn_s_setprio(1); _Pragma("unroll") for (int m = 0; m < 4; ++m) _Pragma("unroll") for (int n = 0; n < 2; ++n) _Pragma("unroll") for (int k = 0; k < 2; ++k) \
;         acc[ai][bj][m][n] = __builtin_amdgcn_mfma_f32_16x16x32_bf16(Bt[n][k], At[m][k], acc[ai][bj][m][n], 0, 0, 0); __builtin_amdgcn_s_setprio(0); } while (0)
; #define PG8_BAR __builtin_amdgcn_s_barrier()
; template <class Epi, class Sched>
; __device__ __forceinline__ void gemm_phase(LAS unsigned char* lds, const Gemm g, const Sched& S, const Epi& E) {
;     ...
;         const bool has_next = S.next(ui + 1, nxt);
;         const char* nA = has_next ? (const char*)g.A + (size_t)nxt.pm * tstep : cA; const char* nB = has_next ? (const char*)g.Bt + (size_t)nxt.pn * tstep : cB;
;         for (int t = 0; t < nt; t += 2) {
;             const bool last = (t == nt - 2);
;             const char* a1 = cA + (size_t)(t + 1) * kstep;
;             const char* a2 = last ? nA : cA + (size_t)(t + 2) * kstep; const char* b2 = last ? nB : cB + (size_t)(t + 2) * kstep;
;             const char* a3 = a2 + kstep; const char* b3 = b2 + kstep;
;             if (last && has_next) S.a_ready(nxt);
;             PG8_LDB(B0, 0, 0); PG8_SCHED; PG8_LDA(At, 0, 0); PG8_STAGE(PG8_SA(1, 1), a1 + hstep, voffA);
;             PG8_WAIT_L(8); PG8_BAR; PG8_WAIT_L(0); PG8_MMA(0, 0, At, B0); PG8_BAR; PG8_SCHED;
;     ...
;         for (int a = 0; a < 2; ++a)
; #pragma unroll
;             for (int b = 0; b < 2; ++b)
; #pragma unroll
;                 for (int m = 0; m < 4; ++m)
; #pragma unroll
;                     for (int n = 0; n < 2; ++n) acc[a][b][m][n] = (f32x4){0.f, 0.f, 0.f, 0.f};
.LBB0_645:
	s_ashr_i32 s75, s74, 31
	v_mov_b64_e32 v[0:1], s[0:1]
	s_lshl_b64 s[16:17], s[74:75], 19
	v_cmp_lt_i64_e32 vcc, s[66:67], v[0:1]
	s_add_u32 s66, s76, s16
	s_addc_u32 s67, s77, s17
	s_and_b64 s[16:17], vcc, exec
	s_cselect_b32 s75, s67, s79
	s_cselect_b32 s16, s66, s78
	s_ashr_i32 s73, s72, 31
	s_lshl_b64 s[18:19], s[72:73], 19
	s_add_u32 s88, s7, s18
	s_addc_u32 s89, s8, s19
	s_and_b64 s[18:19], vcc, exec
	s_cselect_b32 s17, s89, s71
	s_cselect_b32 s73, s88, s70
	s_add_u32 vcc_lo, s78, 0x40080
	s_addc_u32 vcc_hi, s79, 0
	s_add_u32 s18, s70, 0x100
	v_mov_b64_e32 v[82:83], 0
	v_mov_b64_e32 v[84:85], 0
	v_mov_b64_e32 v[86:87], 0
	v_mov_b64_e32 v[88:89], 0
	v_mov_b64_e32 v[98:99], 0
	v_mov_b64_e32 v[100:101], 0
	v_mov_b64_e32 v[102:103], 0
	v_mov_b64_e32 v[104:105], 0
	v_mov_b64_e32 v[114:115], 0
	v_mov_b64_e32 v[116:117], 0
	v_mov_b64_e32 v[118:119], 0
	v_mov_b64_e32 v[120:121], 0
	v_mov_b64_e32 v[122:123], 0
	v_mov_b64_e32 v[124:125], 0
	v_mov_b64_e32 v[126:127], 0
	v_mov_b64_e32 v[128:129], 0
	s_addc_u32 s19, s71, 0
	s_mov_b32 s20, -2
.LBB0_646:
	s_add_u32 s21, vcc_lo, 0xfffc0080
	s_addc_u32 s22, vcc_hi, -1
	s_add_i32 s23, 16, 0x10000
	v_add_u32_e32 v155, s23, v152
	ds_read_b128 v[156:159], v155
	ds_read_b128 v[160:163], v155 offset:1024
	ds_read_b128 v[164:167], v155 offset:2048
	ds_read_b128 v[168:171], v155 offset:3072
	s_cmp_eq_u32 s20, 12
	s_cselect_b32 s79, s75, s22
	s_cselect_b32 s78, s16, s21
	s_cselect_b32 s71, s17, s19
	s_cselect_b32 s70, s73, s18
	v_lshl_add_u64 v[216:217], vcc, 0, v[148:149]
	s_add_i32 m0, s11, 0xc000
	ds_read_b128 v[172:175], v154
	ds_read_b128 v[188:191], v154 offset:1024
	ds_read_b128 v[192:195], v154 offset:2048
	ds_read_b128 v[196:199], v154 offset:3072
	ds_read_b128 v[200:203], v154 offset:4096
	ds_read_b128 v[204:207], v154 offset:5120
	ds_read_b128 v[208:211], v154 offset:6144
	ds_read_b128 v[212:215], v154 offset:7168
	global_load_lds_dwordx4 v[216:217], off
	v_lshl_add_u64 v[216:217], vcc, 0, v[150:151]
	s_add_i32 m0, s11, 0xe000
	s_nop 0
	global_load_lds_dwordx4 v[216:217], off
	s_cmp_lg_u32 s20, -2
	s_cbranch_scc1 .Lzd643
	v_mov_b64_e32 v[66:67], 0
	v_mov_b64_e32 v[68:69], 0
	v_mov_b64_e32 v[70:71], 0
	v_mov_b64_e32 v[72:73], 0
	v_mov_b64_e32 v[74:75], 0
	v_mov_b64_e32 v[76:77], 0
	v_mov_b64_e32 v[78:79], 0
	v_mov_b64_e32 v[80:81], 0
	v_mov_b64_e32 v[90:91], 0
	v_mov_b64_e32 v[92:93], 0
	v_mov_b64_e32 v[94:95], 0
	v_mov_b64_e32 v[96:97], 0
	v_mov_b64_e32 v[106:107], 0
	v_mov_b64_e32 v[108:109], 0
	v_mov_b64_e32 v[110:111], 0
	v_mov_b64_e32 v[112:113], 0
	v_mov_b64_e32 v[18:19], 0
	v_mov_b64_e32 v[20:21], 0
	v_mov_b64_e32 v[22:23], 0
	v_mov_b64_e32 v[24:25], 0
	v_mov_b64_e32 v[34:35], 0
	v_mov_b64_e32 v[36:37], 0
	v_mov_b64_e32 v[38:39], 0
	v_mov_b64_e32 v[40:41], 0
	v_mov_b64_e32 v[50:51], 0
	v_mov_b64_e32 v[52:53], 0
	v_mov_b64_e32 v[54:55], 0
	v_mov_b64_e32 v[56:57], 0
	v_mov_b64_e32 v[58:59], 0
	v_mov_b64_e32 v[60:61], 0
	v_mov_b64_e32 v[62:63], 0
	v_mov_b64_e32 v[64:65], 0
	v_mov_b64_e32 v[0:1], 0
	v_mov_b64_e32 v[2:3], 0
	v_mov_b64_e32 v[4:5], 0
	v_mov_b64_e32 v[6:7], 0
	v_mov_b64_e32 v[10:11], 0
	v_mov_b64_e32 v[12:13], 0
	v_mov_b64_e32 v[14:15], 0
	v_mov_b64_e32 v[16:17], 0
	v_mov_b64_e32 v[26:27], 0
	v_mov_b64_e32 v[28:29], 0
	v_mov_b64_e32 v[30:31], 0
	v_mov_b64_e32 v[32:33], 0
	v_mov_b64_e32 v[42:43], 0
	v_mov_b64_e32 v[44:45], 0
	v_mov_b64_e32 v[46:47], 0
	v_mov_b64_e32 v[48:49], 0
.Lzd643:
	s_waitcnt lgkmcnt(8)
	s_barrier
	s_waitcnt lgkmcnt(0)
	s_setprio 1
	s_waitcnt lgkmcnt(0)
	v_mfma_f32_16x16x32_bf16 v[126:129], v[156:159], v[172:175], v[126:129]
	v_mfma_f32_16x16x32_bf16 v[122:125], v[164:167], v[172:175], v[122:125]
	v_mfma_f32_16x16x32_bf16 v[118:121], v[156:159], v[192:195], v[118:121]
	v_mfma_f32_16x16x32_bf16 v[114:117], v[164:167], v[192:195], v[114:117]
	v_mfma_f32_16x16x32_bf16 v[102:105], v[156:159], v[200:203], v[102:105]
	v_mfma_f32_16x16x32_bf16 v[98:101], v[164:167], v[200:203], v[98:101]
	v_mfma_f32_16x16x32_bf16 v[86:89], v[156:159], v[208:211], v[86:89]
	v_mfma_f32_16x16x32_bf16 v[82:85], v[164:167], v[208:211], v[82:85]
	v_mfma_f32_16x16x32_bf16 v[126:129], v[160:163], v[188:191], v[126:129]
	v_mfma_f32_16x16x32_bf16 v[122:125], v[168:171], v[188:191], v[122:125]
	v_mfma_f32_16x16x32_bf16 v[118:121], v[160:163], v[196:199], v[118:121]
	v_mfma_f32_16x16x32_bf16 v[114:117], v[168:171], v[196:199], v[114:117]
	v_mfma_f32_16x16x32_bf16 v[102:105], v[160:163], v[204:207], v[102:105]
	v_mfma_f32_16x16x32_bf16 v[98:101], v[168:171], v[204:207], v[98:101]
	v_mfma_f32_16x16x32_bf16 v[86:89], v[160:163], v[212:215], v[86:89]
	v_mfma_f32_16x16x32_bf16 v[82:85], v[168:171], v[212:215], v[82:85]
	s_setprio 0
	s_barrier
	s_add_i32 s21, 16, 0x14000
	s_add_i32 s22, s23, s9
	v_add_u32_e32 v155, s21, v152
	v_lshl_add_u64 v[232:233], s[70:71], 0, v[144:145]
	s_mov_b32 m0, s22
	ds_read_b128 v[216:219], v155
	ds_read_b128 v[220:223], v155 offset:1024
	ds_read_b128 v[224:227], v155 offset:2048
	ds_read_b128 v[228:231], v155 offset:3072
	global_load_lds_dwordx4 v[232:233], off
	v_lshl_add_u64 v[234:235], s[70:71], 0, v[140:141]
	s_add_i32 m0, s22, 0x2000
	s_nop 0
	global_load_lds_dwordx4 v[234:235], off
	s_barrier
; #define PG8_STAGE(bufoff, gbase, voff) do { _Pragma("unroll") for (int _i = 0; _i < 2; ++_i) \
;         __builtin_amdgcn_global_load_lds((const unsigned*)((const char*)(gbase) + (voff)[_i]), (LAS unsigned*)(lds + (bufoff) + ldsw + _i * 8192), 16, 0, 0); } while (0)
; #define PG8_LDA(dst, b, h) do { _Pragma("unroll") for (int m = 0; m < 4; ++m) _Pragma("unroll") for (int k = 0; k < 2; ++k) dst[m][k] = *(const LAS bf16x8*)(lds + PG8_SA(b, h) + aoff + m * 2048 + k * 1024); } while (0)
; #define PG8_LDB(dst, b, h) do { _Pragma("unroll") for (int n = 0; n < 2; ++n) _Pragma("unroll") for (int k = 0; k < 2; ++k) dst[n][k] = *(const LAS bf16x8*)(lds + PG8_SB(b, h) + boff + n * 2048 + k * 1024); } while (0)
; #define PG8_MMA(ai, bj, At, Bt) do { __builtin_amdgcn_s_setprio(1); _Pragma("unroll") for (int m = 0; m < 4; ++m) _Pragma("unroll") for (int n = 0; n < 2; ++n) _Pragma("unroll") for (int k = 0; k < 2; ++k) \
;         acc[ai][bj][m][n] = __builtin_amdgcn_mfma_f32_16x16x32_bf16(Bt[n][k], At[m][k], acc[ai][bj][m][n], 0, 0, 0); __builtin_amdgcn_s_setprio(0); } while (0)
; #define PG8_WAIT_V(n) asm volatile("s_waitcnt vmcnt(" #n ")" ::: "memory")
; #define PG8_WAIT_L(n) asm volatile("s_waitcnt lgkmcnt(" #n ")" ::: "memory")
; #define PG8_BAR __builtin_amdgcn_s_barrier()
; #define PG8_SCHED __builtin_amdgcn_sched_barrier(0)
; template <class Epi, class Sched>
; __device__ __forceinline__ void gemm_phase(LAS unsigned char* lds, const Gemm g, const Sched& S, const Epi& E) {
;     ...
;             PG8_BAR; PG8_WAIT_L(0); PG8_MMA(0, 1, At, B1); PG8_BAR;
;             PG8_LDA(At, 0, 1); PG8_STAGE(PG8_SA(0, 0), a2, voffA);
;             PG8_BAR; PG8_WAIT_L(0); PG8_MMA(1, 0, At, B0); PG8_BAR; PG8_SCHED;
;             PG8_STAGE(PG8_SB(0, 1), b2 + hstep, voffB);
;             PG8_WAIT_V(6); PG8_BAR; PG8_MMA(1, 1, At, B1); PG8_BAR;
;             PG8_LDB(B0, 1, 0); PG8_SCHED; PG8_LDA(At, 1, 0); PG8_STAGE(PG8_SA(0, 1), a2 + hstep, voffA);
;             PG8_WAIT_L(8); PG8_BAR; PG8_WAIT_L(0); PG8_MMA(0, 0, At, B0); PG8_BAR; PG8_SCHED;
	s_waitcnt lgkmcnt(0)
	s_setprio 1
	s_waitcnt lgkmcnt(0)
	v_mfma_f32_16x16x32_bf16 v[110:113], v[216:219], v[172:175], v[110:113]
	v_mfma_f32_16x16x32_bf16 v[106:109], v[224:227], v[172:175], v[106:109]
	v_mfma_f32_16x16x32_bf16 v[94:97], v[216:219], v[192:195], v[94:97]
	v_mfma_f32_16x16x32_bf16 v[90:93], v[224:227], v[192:195], v[90:93]
	v_mfma_f32_16x16x32_bf16 v[78:81], v[216:219], v[200:203], v[78:81]
	v_mfma_f32_16x16x32_bf16 v[74:77], v[224:227], v[200:203], v[74:77]
	v_mfma_f32_16x16x32_bf16 v[70:73], v[216:219], v[208:211], v[70:73]
	v_mfma_f32_16x16x32_bf16 v[66:69], v[224:227], v[208:211], v[66:69]
	v_mfma_f32_16x16x32_bf16 v[110:113], v[220:223], v[188:191], v[110:113]
	v_mfma_f32_16x16x32_bf16 v[106:109], v[228:231], v[188:191], v[106:109]
	v_mfma_f32_16x16x32_bf16 v[94:97], v[220:223], v[196:199], v[94:97]
	v_mfma_f32_16x16x32_bf16 v[90:93], v[228:231], v[196:199], v[90:93]
	v_mfma_f32_16x16x32_bf16 v[78:81], v[220:223], v[204:207], v[78:81]
	v_mfma_f32_16x16x32_bf16 v[74:77], v[228:231], v[204:207], v[74:77]
	v_mfma_f32_16x16x32_bf16 v[70:73], v[220:223], v[212:215], v[70:73]
	v_mfma_f32_16x16x32_bf16 v[66:69], v[228:231], v[212:215], v[66:69]
	s_setprio 0
	s_mov_b32 m0, s11
	v_lshl_add_u64 v[236:237], s[78:79], 0, v[146:147]
	s_barrier
	ds_read_b128 v[172:175], v154 offset:16384
	ds_read_b128 v[188:191], v154 offset:17408
	ds_read_b128 v[192:195], v154 offset:18432
	ds_read_b128 v[196:199], v154 offset:19456
	ds_read_b128 v[200:203], v154 offset:20480
	ds_read_b128 v[204:207], v154 offset:21504
	ds_read_b128 v[208:211], v154 offset:22528
	ds_read_b128 v[212:215], v154 offset:23552
	global_load_lds_dwordx4 v[236:237], off
	v_lshl_add_u64 v[238:239], s[78:79], 0, v[142:143]
	s_mov_b32 m0, s41
	s_nop 0
	global_load_lds_dwordx4 v[238:239], off
	s_barrier
	s_waitcnt lgkmcnt(0)
	s_setprio 1
	s_waitcnt lgkmcnt(0)
	v_mfma_f32_16x16x32_bf16 v[62:65], v[156:159], v[172:175], v[62:65]
	v_mfma_f32_16x16x32_bf16 v[58:61], v[164:167], v[172:175], v[58:61]
	v_mfma_f32_16x16x32_bf16 v[54:57], v[156:159], v[192:195], v[54:57]
	v_mfma_f32_16x16x32_bf16 v[50:53], v[164:167], v[192:195], v[50:53]
	v_mfma_f32_16x16x32_bf16 v[38:41], v[156:159], v[200:203], v[38:41]
	v_mfma_f32_16x16x32_bf16 v[34:37], v[164:167], v[200:203], v[34:37]
	v_mfma_f32_16x16x32_bf16 v[22:25], v[156:159], v[208:211], v[22:25]
	v_mfma_f32_16x16x32_bf16 v[18:21], v[164:167], v[208:211], v[18:21]
	v_mfma_f32_16x16x32_bf16 v[62:65], v[160:163], v[188:191], v[62:65]
	v_mfma_f32_16x16x32_bf16 v[58:61], v[168:171], v[188:191], v[58:61]
	v_mfma_f32_16x16x32_bf16 v[54:57], v[160:163], v[196:199], v[54:57]
	v_mfma_f32_16x16x32_bf16 v[50:53], v[168:171], v[196:199], v[50:53]
	v_mfma_f32_16x16x32_bf16 v[38:41], v[160:163], v[204:207], v[38:41]
	v_mfma_f32_16x16x32_bf16 v[34:37], v[168:171], v[204:207], v[34:37]
	v_mfma_f32_16x16x32_bf16 v[22:25], v[160:163], v[212:215], v[22:25]
	v_mfma_f32_16x16x32_bf16 v[18:21], v[168:171], v[212:215], v[18:21]
	s_setprio 0
	s_barrier
	s_add_u32 s22, s70, 0x40000
	s_addc_u32 s23, s71, 0
	s_add_i32 s21, s21, s9
	v_lshl_add_u64 v[156:157], s[22:23], 0, v[144:145]
	s_mov_b32 m0, s21
	s_nop 0
	global_load_lds_dwordx4 v[156:157], off
	v_lshl_add_u64 v[156:157], s[22:23], 0, v[140:141]
	s_add_i32 m0, s21, 0x2000
	s_nop 0
	global_load_lds_dwordx4 v[156:157], off
	s_waitcnt vmcnt(6)
	s_barrier
	s_setprio 1
	v_mfma_f32_16x16x32_bf16 v[46:49], v[216:219], v[172:175], v[46:49]
	v_mfma_f32_16x16x32_bf16 v[42:45], v[224:227], v[172:175], v[42:45]
	v_mfma_f32_16x16x32_bf16 v[30:33], v[216:219], v[192:195], v[30:33]
	v_mfma_f32_16x16x32_bf16 v[26:29], v[224:227], v[192:195], v[26:29]
	v_mfma_f32_16x16x32_bf16 v[14:17], v[216:219], v[200:203], v[14:17]
	v_mfma_f32_16x16x32_bf16 v[10:13], v[224:227], v[200:203], v[10:13]
	v_mfma_f32_16x16x32_bf16 v[4:7], v[216:219], v[208:211], v[4:7]
	v_mfma_f32_16x16x32_bf16 v[0:3], v[224:227], v[208:211], v[0:3]
	v_mfma_f32_16x16x32_bf16 v[46:49], v[220:223], v[188:191], v[46:49]
	v_mfma_f32_16x16x32_bf16 v[42:45], v[228:231], v[188:191], v[42:45]
	v_mfma_f32_16x16x32_bf16 v[30:33], v[220:223], v[196:199], v[30:33]
	v_mfma_f32_16x16x32_bf16 v[26:29], v[228:231], v[196:199], v[26:29]
	v_mfma_f32_16x16x32_bf16 v[14:17], v[220:223], v[204:207], v[14:17]
	v_mfma_f32_16x16x32_bf16 v[10:13], v[228:231], v[204:207], v[10:13]
	v_mfma_f32_16x16x32_bf16 v[4:7], v[220:223], v[212:215], v[4:7]
	v_mfma_f32_16x16x32_bf16 v[0:3], v[228:231], v[212:215], v[0:3]
	s_setprio 0
	s_add_i32 s21, 16, 0x18000
	v_add_u32_e32 v155, s21, v152
	s_barrier
	ds_read_b128 v[156:159], v155
	ds_read_b128 v[160:163], v155 offset:1024
	ds_read_b128 v[164:167], v155 offset:2048
	ds_read_b128 v[168:171], v155 offset:3072
	s_add_u32 s22, s78, 0x40000
	s_addc_u32 s23, s79, 0
	s_mov_b32 m0, s12
	v_lshl_add_u64 v[216:217], s[22:23], 0, v[146:147]
	ds_read_b128 v[172:175], v154 offset:32768
	ds_read_b128 v[188:191], v154 offset:33792
	ds_read_b128 v[192:195], v154 offset:34816
	ds_read_b128 v[196:199], v154 offset:35840
	ds_read_b128 v[200:203], v154 offset:36864
	ds_read_b128 v[204:207], v154 offset:37888
	ds_read_b128 v[208:211], v154 offset:38912
	ds_read_b128 v[212:215], v154 offset:39936
	global_load_lds_dwordx4 v[216:217], off
	v_lshl_add_u64 v[216:217], s[22:23], 0, v[142:143]
	s_mov_b32 m0, s13
	s_nop 0
	global_load_lds_dwordx4 v[216:217], off
	s_waitcnt lgkmcnt(8)
	s_barrier
; #define PG8_STAGE(bufoff, gbase, voff) do { _Pragma("unroll") for (int _i = 0; _i < 2; ++_i) \
;         __builtin_amdgcn_global_load_lds((const unsigned*)((const char*)(gbase) + (voff)[_i]), (LAS unsigned*)(lds + (bufoff) + ldsw + _i * 8192), 16, 0, 0); } while (0)
; #define PG8_LDA(dst, b, h) do { _Pragma("unroll") for (int m = 0; m < 4; ++m) _Pragma("unroll") for (int k = 0; k < 2; ++k) dst[m][k] = *(const LAS bf16x8*)(lds + PG8_SA(b, h) + aoff + m * 2048 + k * 1024); } while (0)
; #define PG8_LDB(dst, b, h) do { _Pragma("unroll") for (int n = 0; n < 2; ++n) _Pragma("unroll") for (int k = 0; k < 2; ++k) dst[n][k] = *(const LAS bf16x8*)(lds + PG8_SB(b, h) + boff + n * 2048 + k * 1024); } while (0)
; #define PG8_MMA(ai, bj, At, Bt) do { __builtin_amdgcn_s_setprio(1); _Pragma("unroll") for (int m = 0; m < 4; ++m) _Pragma("unroll") for (int n = 0; n < 2; ++n) _Pragma("unroll") for (int k = 0; k < 2; ++k) \
;         acc[ai][bj][m][n] = __builtin_amdgcn_mfma_f32_16x16x32_bf16(Bt[n][k], At[m][k], acc[ai][bj][m][n], 0, 0, 0); __builtin_amdgcn_s_setprio(0); } while (0)
; #define PG8_WAIT_V(n) asm volatile("s_waitcnt vmcnt(" #n ")" ::: "memory")
; #define PG8_WAIT_L(n) asm volatile("s_waitcnt lgkmcnt(" #n ")" ::: "memory")
; #define PG8_BAR __builtin_amdgcn_s_barrier()
; #define PG8_SCHED __builtin_amdgcn_sched_barrier(0)
; template <class Epi, class Sched>
; __device__ __forceinline__ void gemm_phase(LAS unsigned char* lds, const Gemm g, const Sched& S, const Epi& E) {
;     ...
;             PG8_WAIT_L(8); PG8_BAR; PG8_WAIT_L(0); PG8_MMA(0, 0, At, B0); PG8_BAR; PG8_SCHED;
;             PG8_LDB(B1, 1, 1); PG8_STAGE(PG8_SB(1, 0), b3, voffB);
;             PG8_BAR; PG8_WAIT_L(0); PG8_MMA(0, 1, At, B1); PG8_BAR;
;             PG8_LDA(At, 1, 1); PG8_STAGE(PG8_SA(1, 0), a3, voffA);
;             PG8_BAR; PG8_WAIT_L(0); PG8_MMA(1, 0, At, B0); PG8_BAR; PG8_SCHED;
;             PG8_STAGE(PG8_SB(1, 1), b3 + hstep, voffB);
;             PG8_WAIT_V(6); PG8_BAR; PG8_MMA(1, 1, At, B1); PG8_BAR;
	s_waitcnt lgkmcnt(0)
	s_setprio 1
	s_waitcnt lgkmcnt(0)
	v_mfma_f32_16x16x32_bf16 v[126:129], v[156:159], v[172:175], v[126:129]
	v_mfma_f32_16x16x32_bf16 v[122:125], v[164:167], v[172:175], v[122:125]
	v_mfma_f32_16x16x32_bf16 v[118:121], v[156:159], v[192:195], v[118:121]
	v_mfma_f32_16x16x32_bf16 v[114:117], v[164:167], v[192:195], v[114:117]
	v_mfma_f32_16x16x32_bf16 v[102:105], v[156:159], v[200:203], v[102:105]
	v_mfma_f32_16x16x32_bf16 v[98:101], v[164:167], v[200:203], v[98:101]
	v_mfma_f32_16x16x32_bf16 v[86:89], v[156:159], v[208:211], v[86:89]
	v_mfma_f32_16x16x32_bf16 v[82:85], v[164:167], v[208:211], v[82:85]
	v_mfma_f32_16x16x32_bf16 v[126:129], v[160:163], v[188:191], v[126:129]
	v_mfma_f32_16x16x32_bf16 v[122:125], v[168:171], v[188:191], v[122:125]
	v_mfma_f32_16x16x32_bf16 v[118:121], v[160:163], v[196:199], v[118:121]
	v_mfma_f32_16x16x32_bf16 v[114:117], v[168:171], v[196:199], v[114:117]
	v_mfma_f32_16x16x32_bf16 v[102:105], v[160:163], v[204:207], v[102:105]
	v_mfma_f32_16x16x32_bf16 v[98:101], v[168:171], v[204:207], v[98:101]
	v_mfma_f32_16x16x32_bf16 v[86:89], v[160:163], v[212:215], v[86:89]
	v_mfma_f32_16x16x32_bf16 v[82:85], v[168:171], v[212:215], v[82:85]
	s_setprio 0
	s_barrier
	s_add_i32 s78, 16, 0x1c000
	s_add_i32 s21, s21, s9
	v_add_u32_e32 v155, s78, v152
	v_lshl_add_u64 v[232:233], v[232:233], 0, s[94:95]
	s_mov_b32 m0, s21
	ds_read_b128 v[216:219], v155
	ds_read_b128 v[220:223], v155 offset:1024
	ds_read_b128 v[224:227], v155 offset:2048
	ds_read_b128 v[228:231], v155 offset:3072
	global_load_lds_dwordx4 v[232:233], off
	v_lshl_add_u64 v[232:233], v[234:235], 0, s[94:95]
	s_add_i32 m0, s21, 0x2000
	s_nop 0
	global_load_lds_dwordx4 v[232:233], off
	s_barrier
	s_waitcnt lgkmcnt(0)
	s_setprio 1
	s_waitcnt lgkmcnt(0)
	v_mfma_f32_16x16x32_bf16 v[110:113], v[216:219], v[172:175], v[110:113]
	v_mfma_f32_16x16x32_bf16 v[106:109], v[224:227], v[172:175], v[106:109]
	v_mfma_f32_16x16x32_bf16 v[94:97], v[216:219], v[192:195], v[94:97]
	v_mfma_f32_16x16x32_bf16 v[90:93], v[224:227], v[192:195], v[90:93]
	v_mfma_f32_16x16x32_bf16 v[78:81], v[216:219], v[200:203], v[78:81]
	v_mfma_f32_16x16x32_bf16 v[74:77], v[224:227], v[200:203], v[74:77]
	v_mfma_f32_16x16x32_bf16 v[70:73], v[216:219], v[208:211], v[70:73]
	v_mfma_f32_16x16x32_bf16 v[66:69], v[224:227], v[208:211], v[66:69]
	v_mfma_f32_16x16x32_bf16 v[110:113], v[220:223], v[188:191], v[110:113]
	v_mfma_f32_16x16x32_bf16 v[106:109], v[228:231], v[188:191], v[106:109]
	v_mfma_f32_16x16x32_bf16 v[94:97], v[220:223], v[196:199], v[94:97]
	v_mfma_f32_16x16x32_bf16 v[90:93], v[228:231], v[196:199], v[90:93]
	v_mfma_f32_16x16x32_bf16 v[78:81], v[220:223], v[204:207], v[78:81]
	v_mfma_f32_16x16x32_bf16 v[74:77], v[228:231], v[204:207], v[74:77]
	v_mfma_f32_16x16x32_bf16 v[70:73], v[220:223], v[212:215], v[70:73]
	v_mfma_f32_16x16x32_bf16 v[66:69], v[228:231], v[212:215], v[66:69]
	s_setprio 0
	s_mov_b32 m0, s14
	v_lshl_add_u64 v[232:233], v[236:237], 0, s[94:95]
	s_barrier
	ds_read_b128 v[172:175], v154 offset:49152
	ds_read_b128 v[188:191], v154 offset:50176
	ds_read_b128 v[192:195], v154 offset:51200
	ds_read_b128 v[196:199], v154 offset:52224
	ds_read_b128 v[200:203], v154 offset:53248
	ds_read_b128 v[204:207], v154 offset:54272
	ds_read_b128 v[208:211], v154 offset:55296
	ds_read_b128 v[212:215], v154 offset:56320
	global_load_lds_dwordx4 v[232:233], off
	v_lshl_add_u64 v[232:233], v[238:239], 0, s[94:95]
	s_mov_b32 m0, s15
	s_nop 0
	global_load_lds_dwordx4 v[232:233], off
	s_barrier
	s_waitcnt lgkmcnt(0)
	s_setprio 1
	s_waitcnt lgkmcnt(0)
	v_mfma_f32_16x16x32_bf16 v[62:65], v[156:159], v[172:175], v[62:65]
	v_mfma_f32_16x16x32_bf16 v[58:61], v[164:167], v[172:175], v[58:61]
	v_mfma_f32_16x16x32_bf16 v[54:57], v[156:159], v[192:195], v[54:57]
	v_mfma_f32_16x16x32_bf16 v[50:53], v[164:167], v[192:195], v[50:53]
	v_mfma_f32_16x16x32_bf16 v[38:41], v[156:159], v[200:203], v[38:41]
	v_mfma_f32_16x16x32_bf16 v[34:37], v[164:167], v[200:203], v[34:37]
	v_mfma_f32_16x16x32_bf16 v[22:25], v[156:159], v[208:211], v[22:25]
	v_mfma_f32_16x16x32_bf16 v[18:21], v[164:167], v[208:211], v[18:21]
	v_mfma_f32_16x16x32_bf16 v[62:65], v[160:163], v[188:191], v[62:65]
	v_mfma_f32_16x16x32_bf16 v[58:61], v[168:171], v[188:191], v[58:61]
	v_mfma_f32_16x16x32_bf16 v[54:57], v[160:163], v[196:199], v[54:57]
	v_mfma_f32_16x16x32_bf16 v[50:53], v[168:171], v[196:199], v[50:53]
	v_mfma_f32_16x16x32_bf16 v[38:41], v[160:163], v[204:207], v[38:41]
	v_mfma_f32_16x16x32_bf16 v[34:37], v[168:171], v[204:207], v[34:37]
	v_mfma_f32_16x16x32_bf16 v[22:25], v[160:163], v[212:215], v[22:25]
	v_mfma_f32_16x16x32_bf16 v[18:21], v[168:171], v[212:215], v[18:21]
	s_setprio 0
	s_barrier
	s_add_u32 s22, s70, 0x40080
	s_addc_u32 s23, s71, 0
	s_add_i32 s21, s78, s9
	v_lshl_add_u64 v[156:157], s[22:23], 0, v[144:145]
	s_mov_b32 m0, s21
	s_nop 0
	global_load_lds_dwordx4 v[156:157], off
	v_lshl_add_u64 v[156:157], s[22:23], 0, v[140:141]
	s_add_i32 m0, s21, 0x2000
	s_nop 0
	global_load_lds_dwordx4 v[156:157], off
	s_waitcnt vmcnt(6)
	s_barrier
; __device__ __forceinline__ unsigned pk_bf16(float a, float b) { f32x2 v = {a, b}; bf2_t r = __builtin_convertvector(v, bf2_t); return __builtin_bit_cast(unsigned, r); }
; #define PG8_MMA(ai, bj, At, Bt) do { __builtin_amdgcn_s_setprio(1); _Pragma("unroll") for (int m = 0; m < 4; ++m) _Pragma("unroll") for (int n = 0; n < 2; ++n) _Pragma("unroll") for (int k = 0; k < 2; ++k) \
;         acc[ai][bj][m][n] = __builtin_amdgcn_mfma_f32_16x16x32_bf16(Bt[n][k], At[m][k], acc[ai][bj][m][n], 0, 0, 0); __builtin_amdgcn_s_setprio(0); } while (0)
;     __device__ __forceinline__ void operator()(const f32x4 (&acc)[2][2][4][2], const Unit& u, int wr, int wc, int fr, int fq) const {
;         const int row0 = u.pm * BM + wr * 64 + fr; int colt = u.pn * BM; bf16_t* base = O;
;         if (split_cols) { const int t = colt / split_cols; base += (size_t)t * split_stride; colt -= t * split_cols; }
;         const int col0 = colt + wc * 32 + 8 * fq;
; #pragma unroll
;         for (int ai = 0; ai < 2; ++ai)
; #pragma unroll
;             for (int m = 0; m < 4; ++m) { const int row = row0 + ai * HALF + m * 16;
;                 bf16_t* rowp = slot_stride ? base + (size_t)(colt >> 7) * slot_stride + (size_t)row * 128 + wc * 32 + 8 * fq : base + (size_t)row * ldc + col0;
; #pragma unroll
;                 for (int bj = 0; bj < 2; ++bj) { const f32x4 v0 = acc[ai][bj][m][0], v1 = acc[ai][bj][m][1];
;                     u32x4 w; w.x = pk_bf16(v0[0], v0[1]); w.y = pk_bf16(v0[2], v0[3]); w.z = pk_bf16(v1[0], v1[1]); w.w = pk_bf16(v1[2], v1[3]);
;                     *(u32x4*)(rowp + (slot_stride ? (size_t)bj * slot_stride : (size_t)bj * HALF)) = w; } }
; template <class Epi, class Sched>
; __device__ __forceinline__ void gemm_phase(LAS unsigned char* lds, const Gemm g, const Sched& S, const Epi& E) {
;     ...
;             PG8_WAIT_V(6); PG8_BAR; PG8_MMA(1, 1, At, B1); PG8_BAR;
;         }
;         E(acc, cur, wr, wc, fr, fq); S.done(cur);
;         if (!has_next) break;
; #pragma unroll
;         for (int a = 0; a < 2; ++a)
; #pragma unroll
;             for (int b = 0; b < 2; ++b)
; #pragma unroll
;                 for (int m = 0; m < 4; ++m)
; #pragma unroll
;                     for (int n = 0; n < 2; ++n) acc[a][b][m][n] = (f32x4){0.f, 0.f, 0.f, 0.f};
;         cur = nxt; cA = nA; cB = nB; ++ui;
;     }
;     PG8_WAIT_V(0);
;     if (wr == 0) PG8_BAR;
	s_setprio 1
	v_mfma_f32_16x16x32_bf16 v[46:49], v[216:219], v[172:175], v[46:49]
	v_mfma_f32_16x16x32_bf16 v[42:45], v[224:227], v[172:175], v[42:45]
	v_mfma_f32_16x16x32_bf16 v[30:33], v[216:219], v[192:195], v[30:33]
	v_mfma_f32_16x16x32_bf16 v[26:29], v[224:227], v[192:195], v[26:29]
	v_mfma_f32_16x16x32_bf16 v[14:17], v[216:219], v[200:203], v[14:17]
	v_mfma_f32_16x16x32_bf16 v[10:13], v[224:227], v[200:203], v[10:13]
	v_mfma_f32_16x16x32_bf16 v[4:7], v[216:219], v[208:211], v[4:7]
	v_mfma_f32_16x16x32_bf16 v[0:3], v[224:227], v[208:211], v[0:3]
	v_mfma_f32_16x16x32_bf16 v[46:49], v[220:223], v[188:191], v[46:49]
	v_mfma_f32_16x16x32_bf16 v[42:45], v[228:231], v[188:191], v[42:45]
	v_mfma_f32_16x16x32_bf16 v[30:33], v[220:223], v[196:199], v[30:33]
	v_mfma_f32_16x16x32_bf16 v[26:29], v[228:231], v[196:199], v[26:29]
	v_mfma_f32_16x16x32_bf16 v[14:17], v[220:223], v[204:207], v[14:17]
	v_mfma_f32_16x16x32_bf16 v[10:13], v[228:231], v[204:207], v[10:13]
	v_mfma_f32_16x16x32_bf16 v[4:7], v[220:223], v[212:215], v[4:7]
	v_mfma_f32_16x16x32_bf16 v[0:3], v[228:231], v[212:215], v[0:3]
	s_setprio 0
	s_add_i32 s20, s20, 2
	s_add_u32 vcc_lo, vcc_lo, 0x100
	s_addc_u32 vcc_hi, vcc_hi, 0
	s_add_u32 s18, s18, 0x100
	s_addc_u32 s19, s19, 0
	s_cmp_gt_u32 s20, 13
	s_barrier
	s_cbranch_scc0 .LBB0_646
	s_mul_hi_i32 s16, s40, 0x2e8ba2e9
	s_lshr_b32 s17, s16, 31
	s_ashr_i32 s16, s16, 1
	s_add_i32 s19, s16, s17
	s_lshl_b32 s18, s40, 8
	s_mul_i32 s16, s19, 0xbb00000
	s_mul_hi_i32 s17, s19, 0xbb00000
	s_add_u32 s16, s82, s16
	s_mulk_i32 s19, 0xf500
	s_addc_u32 s17, s83, s17
	s_add_i32 s19, s19, s18
	v_or_b32_e32 v156, s19, v153
	v_lshl_add_u32 v155, s42, 8, v9
	v_ashrrev_i32_e32 v157, 31, v156
	v_lshl_add_u64 v[156:157], v[156:157], 1, s[16:17]
	v_cvt_pk_bf16_f32 v70, v70, v71
	v_cvt_pk_bf16_f32 v71, v72, v73
	v_cvt_pk_bf16_f32 v72, v66, v67
	v_add_u32_e32 v66, 0x80, v155
	v_mad_i64_i32 v[158:159], s[16:17], v155, s81, v[156:157]
	v_cvt_pk_bf16_f32 v110, v110, v111
	v_cvt_pk_bf16_f32 v111, v112, v113
	v_cvt_pk_bf16_f32 v112, v106, v107
	v_cvt_pk_bf16_f32 v113, v108, v109
	v_or_b32_e32 v106, 16, v155
	v_mad_i64_i32 v[66:67], s[16:17], v66, s81, v[156:157]
	v_cvt_pk_bf16_f32 v46, v46, v47
	v_cvt_pk_bf16_f32 v47, v48, v49
	v_cvt_pk_bf16_f32 v48, v42, v43
	v_cvt_pk_bf16_f32 v49, v44, v45
	v_add_u32_e32 v42, 0x90, v155
	global_store_dwordx4 v[158:159], v[110:113], off offset:256
	v_cvt_pk_bf16_f32 v94, v94, v95
	v_cvt_pk_bf16_f32 v95, v96, v97
	v_mad_i64_i32 v[110:111], s[16:17], v106, s81, v[156:157]
	v_cvt_pk_bf16_f32 v96, v90, v91
	v_cvt_pk_bf16_f32 v97, v92, v93
	v_or_b32_e32 v90, 32, v155
	global_store_dwordx4 v[66:67], v[46:49], off offset:256
	v_cvt_pk_bf16_f32 v30, v30, v31
	v_cvt_pk_bf16_f32 v31, v32, v33
	v_mad_i64_i32 v[46:47], s[16:17], v42, s81, v[156:157]
	v_cvt_pk_bf16_f32 v32, v26, v27
	v_cvt_pk_bf16_f32 v33, v28, v29
	v_add_u32_e32 v26, 0xa0, v155
	global_store_dwordx4 v[110:111], v[94:97], off offset:256
	v_cvt_pk_bf16_f32 v78, v78, v79
	v_cvt_pk_bf16_f32 v79, v80, v81
	v_mad_i64_i32 v[94:95], s[16:17], v90, s81, v[156:157]
	v_cvt_pk_bf16_f32 v80, v74, v75
	v_cvt_pk_bf16_f32 v81, v76, v77
	v_or_b32_e32 v74, 48, v155
	global_store_dwordx4 v[46:47], v[30:33], off offset:256
	v_cvt_pk_bf16_f32 v14, v14, v15
	v_cvt_pk_bf16_f32 v15, v16, v17
	v_mad_i64_i32 v[30:31], s[16:17], v26, s81, v[156:157]
	v_cvt_pk_bf16_f32 v16, v10, v11
	v_cvt_pk_bf16_f32 v17, v12, v13
	v_add_u32_e32 v10, 0xb0, v155
	v_cvt_pk_bf16_f32 v126, v126, v127
	v_cvt_pk_bf16_f32 v127, v128, v129
	v_cvt_pk_bf16_f32 v128, v122, v123
	v_cvt_pk_bf16_f32 v129, v124, v125
	v_cvt_pk_bf16_f32 v106, v118, v119
	v_cvt_pk_bf16_f32 v107, v120, v121
	v_cvt_pk_bf16_f32 v108, v114, v115
	v_cvt_pk_bf16_f32 v109, v116, v117
	v_cvt_pk_bf16_f32 v90, v102, v103
	v_cvt_pk_bf16_f32 v91, v104, v105
	v_cvt_pk_bf16_f32 v92, v98, v99
	v_cvt_pk_bf16_f32 v93, v100, v101
	global_store_dwordx4 v[94:95], v[78:81], off offset:256
	v_cvt_pk_bf16_f32 v75, v88, v89
	v_cvt_pk_bf16_f32 v76, v82, v83
	v_mad_i64_i32 v[78:79], s[16:17], v74, s81, v[156:157]
	v_cvt_pk_bf16_f32 v74, v86, v87
	v_cvt_pk_bf16_f32 v77, v84, v85
	v_cvt_pk_bf16_f32 v73, v68, v69
	v_cvt_pk_bf16_f32 v62, v62, v63
	v_cvt_pk_bf16_f32 v63, v64, v65
	v_cvt_pk_bf16_f32 v64, v58, v59
	v_cvt_pk_bf16_f32 v65, v60, v61
	v_cvt_pk_bf16_f32 v42, v54, v55
	v_cvt_pk_bf16_f32 v43, v56, v57
	v_cvt_pk_bf16_f32 v44, v50, v51
	v_cvt_pk_bf16_f32 v45, v52, v53
	v_cvt_pk_bf16_f32 v26, v38, v39
	v_cvt_pk_bf16_f32 v27, v40, v41
	v_cvt_pk_bf16_f32 v28, v34, v35
	v_cvt_pk_bf16_f32 v29, v36, v37
	global_store_dwordx4 v[30:31], v[14:17], off offset:256
	v_cvt_pk_bf16_f32 v11, v24, v25
	v_cvt_pk_bf16_f32 v12, v18, v19
	v_mad_i64_i32 v[14:15], s[16:17], v10, s81, v[156:157]
	v_cvt_pk_bf16_f32 v10, v22, v23
	v_cvt_pk_bf16_f32 v13, v20, v21
	v_cvt_pk_bf16_f32 v4, v4, v5
	v_cvt_pk_bf16_f32 v5, v6, v7
	v_cvt_pk_bf16_f32 v6, v0, v1
	v_cvt_pk_bf16_f32 v7, v2, v3
	s_and_b64 vcc, exec, s[38:39]
	s_mov_b32 s40, s72
	s_mov_b32 s42, s74
	s_mov_b64 s[70:71], s[88:89]
	s_mov_b64 s[78:79], s[66:67]
	global_store_dwordx4 v[158:159], v[126:129], off
	global_store_dwordx4 v[110:111], v[106:109], off
	global_store_dwordx4 v[94:95], v[90:93], off
	global_store_dwordx4 v[78:79], v[74:77], off
	global_store_dwordx4 v[78:79], v[70:73], off offset:256
	global_store_dwordx4 v[66:67], v[62:65], off
	global_store_dwordx4 v[46:47], v[42:45], off
	global_store_dwordx4 v[30:31], v[26:29], off
	global_store_dwordx4 v[14:15], v[10:13], off
	global_store_dwordx4 v[14:15], v[4:7], off offset:256
	s_cbranch_vccz .LBB0_643
	s_waitcnt vmcnt(0)
	s_cmpk_gt_u32 s6, 0xff
	s_cbranch_scc1 .LBB0_650
	s_barrier

; #define PG8_STAGE(bufoff, gbase, voff) do { _Pragma("unroll") for (int _i = 0; _i < 2; ++_i) \
;         __builtin_amdgcn_global_load_lds((const unsigned*)((const char*)(gbase) + (voff)[_i]), (LAS unsigned*)(lds + (bufoff) + ldsw + _i * 8192), 16, 0, 0); } while (0)
; #define PG8_LDA(dst, b, h) do { _Pragma("unroll") for (int m = 0; m < 4; ++m) _Pragma("unroll") for (int k = 0; k < 2; ++k) dst[m][k] = *(const LAS bf16x8*)(lds + PG8_SA(b, h) + aoff + m * 2048 + k * 1024); } while (0)
; #define PG8_LDB(dst, b, h) do { _Pragma("unroll") for (int n = 0; n < 2; ++n) _Pragma("unroll") for (int k = 0; k < 2; ++k) dst[n][k] = *(const LAS bf16x8*)(lds + PG8_SB(b, h) + boff + n * 2048 + k * 1024); } while (0)
; #define PG8_MMA(ai, bj, At, Bt) do { __builtin_amdgcn_s_setprio(1); _Pragma("unroll") for (int m = 0; m < 4; ++m) _Pragma("unroll") for (int n = 0; n < 2; ++n) _Pragma("unroll") for (int k = 0; k < 2; ++k) \
;         acc[ai][bj][m][n] = __builtin_amdgcn_mfma_f32_16x16x32_bf16(Bt[n][k], At[m][k], acc[ai][bj][m][n], 0, 0, 0); __builtin_amdgcn_s_setprio(0); } while (0)
; #define PG8_WAIT_L(n) asm volatile("s_waitcnt lgkmcnt(" #n ")" ::: "memory")
; #define PG8_BAR __builtin_amdgcn_s_barrier()
; template <class Epi, class Sched>
; __device__ __forceinline__ void gemm_phase(LAS unsigned char* lds, const Gemm g, const Sched& S, const Epi& E) {
;     ...
;         for (int t = 0; t < nt; t += 2) {
;             const bool last = (t == nt - 2);
;             const char* a1 = cA + (size_t)(t + 1) * kstep;
;             const char* a2 = last ? nA : cA + (size_t)(t + 2) * kstep; const char* b2 = last ? nB : cB + (size_t)(t + 2) * kstep;
;             const char* a3 = a2 + kstep; const char* b3 = b2 + kstep;
;             if (last && has_next) S.a_ready(nxt);
;             PG8_LDB(B0, 0, 0); PG8_SCHED; PG8_LDA(At, 0, 0); PG8_STAGE(PG8_SA(1, 1), a1 + hstep, voffA);
;             PG8_WAIT_L(8); PG8_BAR; PG8_WAIT_L(0); PG8_MMA(0, 0, At, B0); PG8_BAR; PG8_SCHED;
;             PG8_LDB(B1, 0, 1); PG8_STAGE(PG8_SB(0, 0), b2, voffB);
;             PG8_BAR; PG8_WAIT_L(0); PG8_MMA(0, 1, At, B1); PG8_BAR;
;     ...
;         for (int a = 0; a < 2; ++a)
; #pragma unroll
;             for (int b = 0; b < 2; ++b)
; #pragma unroll
;                 for (int m = 0; m < 4; ++m)
; #pragma unroll
;                     for (int n = 0; n < 2; ++n) acc[a][b][m][n] = (f32x4){0.f, 0.f, 0.f, 0.f};
.LBB0_824:
	s_add_u32 s16, s72, 0x100
	v_mov_b64_e32 v[82:83], 0
	v_mov_b64_e32 v[84:85], 0
	v_mov_b64_e32 v[86:87], 0
	v_mov_b64_e32 v[88:89], 0
	v_mov_b64_e32 v[98:99], 0
	v_mov_b64_e32 v[100:101], 0
	v_mov_b64_e32 v[102:103], 0
	v_mov_b64_e32 v[104:105], 0
	v_mov_b64_e32 v[114:115], 0
	v_mov_b64_e32 v[116:117], 0
	v_mov_b64_e32 v[118:119], 0
	v_mov_b64_e32 v[120:121], 0
	v_mov_b64_e32 v[122:123], 0
	v_mov_b64_e32 v[124:125], 0
	v_mov_b64_e32 v[126:127], 0
	v_mov_b64_e32 v[128:129], 0
	s_addc_u32 s17, s73, 0
	s_mov_b32 s18, -2
.LBB0_825:
	s_add_u32 s72, s42, 0x100
	s_addc_u32 s73, s43, 0
	s_add_i32 s19, 16, 0x10000
	v_add_u32_e32 v155, s19, v152
	ds_read_b128 v[156:159], v155
	ds_read_b128 v[160:163], v155 offset:1024
	ds_read_b128 v[164:167], v155 offset:2048
	ds_read_b128 v[168:171], v155 offset:3072
	s_cmp_eq_u32 s18, 40
	s_cselect_b32 s71, s41, s73
	s_cselect_b32 s70, s40, s72
	s_cselect_b32 s67, s1, s17
	s_cselect_b32 s66, s0, s16
	v_lshl_add_u64 v[216:217], s[42:43], 0, v[148:149]
	s_add_i32 m0, s11, 0xc000
	ds_read_b128 v[172:175], v154
	ds_read_b128 v[188:191], v154 offset:1024
	ds_read_b128 v[192:195], v154 offset:2048
	ds_read_b128 v[196:199], v154 offset:3072
	ds_read_b128 v[200:203], v154 offset:4096
	ds_read_b128 v[204:207], v154 offset:5120
	ds_read_b128 v[208:211], v154 offset:6144
	ds_read_b128 v[212:215], v154 offset:7168
	global_load_lds_dwordx4 v[216:217], off
	v_lshl_add_u64 v[216:217], s[42:43], 0, v[150:151]
	s_add_i32 m0, s11, 0xe000
	s_nop 0
	global_load_lds_dwordx4 v[216:217], off
	s_cmp_lg_u32 s18, -2
	s_cbranch_scc1 .Lzd818
	v_mov_b64_e32 v[66:67], 0
	v_mov_b64_e32 v[68:69], 0
	v_mov_b64_e32 v[70:71], 0
	v_mov_b64_e32 v[72:73], 0
	v_mov_b64_e32 v[74:75], 0
	v_mov_b64_e32 v[76:77], 0
	v_mov_b64_e32 v[78:79], 0
	v_mov_b64_e32 v[80:81], 0
	v_mov_b64_e32 v[90:91], 0
	v_mov_b64_e32 v[92:93], 0
	v_mov_b64_e32 v[94:95], 0
	v_mov_b64_e32 v[96:97], 0
	v_mov_b64_e32 v[106:107], 0
	v_mov_b64_e32 v[108:109], 0
	v_mov_b64_e32 v[110:111], 0
	v_mov_b64_e32 v[112:113], 0
	v_mov_b64_e32 v[18:19], 0
	v_mov_b64_e32 v[20:21], 0
	v_mov_b64_e32 v[22:23], 0
	v_mov_b64_e32 v[24:25], 0
	v_mov_b64_e32 v[34:35], 0
	v_mov_b64_e32 v[36:37], 0
	v_mov_b64_e32 v[38:39], 0
	v_mov_b64_e32 v[40:41], 0
	v_mov_b64_e32 v[50:51], 0
	v_mov_b64_e32 v[52:53], 0
	v_mov_b64_e32 v[54:55], 0
	v_mov_b64_e32 v[56:57], 0
	v_mov_b64_e32 v[58:59], 0
	v_mov_b64_e32 v[60:61], 0
	v_mov_b64_e32 v[62:63], 0
	v_mov_b64_e32 v[64:65], 0
	v_mov_b64_e32 v[0:1], 0
	v_mov_b64_e32 v[2:3], 0
	v_mov_b64_e32 v[4:5], 0
	v_mov_b64_e32 v[6:7], 0
	v_mov_b64_e32 v[10:11], 0
	v_mov_b64_e32 v[12:13], 0
	v_mov_b64_e32 v[14:15], 0
	v_mov_b64_e32 v[16:17], 0
	v_mov_b64_e32 v[26:27], 0
	v_mov_b64_e32 v[28:29], 0
	v_mov_b64_e32 v[30:31], 0
	v_mov_b64_e32 v[32:33], 0
	v_mov_b64_e32 v[42:43], 0
	v_mov_b64_e32 v[44:45], 0
	v_mov_b64_e32 v[46:47], 0
	v_mov_b64_e32 v[48:49], 0
.Lzd818:
	s_waitcnt lgkmcnt(8)
	s_barrier
	s_waitcnt lgkmcnt(0)
	s_setprio 1
	s_waitcnt lgkmcnt(0)
	v_mfma_f32_16x16x32_bf16 v[126:129], v[156:159], v[172:175], v[126:129]
	v_mfma_f32_16x16x32_bf16 v[122:125], v[164:167], v[172:175], v[122:125]
	v_mfma_f32_16x16x32_bf16 v[118:121], v[156:159], v[192:195], v[118:121]
	v_mfma_f32_16x16x32_bf16 v[114:117], v[164:167], v[192:195], v[114:117]
	v_mfma_f32_16x16x32_bf16 v[102:105], v[156:159], v[200:203], v[102:105]
	v_mfma_f32_16x16x32_bf16 v[98:101], v[164:167], v[200:203], v[98:101]
	v_mfma_f32_16x16x32_bf16 v[86:89], v[156:159], v[208:211], v[86:89]
	v_mfma_f32_16x16x32_bf16 v[82:85], v[164:167], v[208:211], v[82:85]
	v_mfma_f32_16x16x32_bf16 v[126:129], v[160:163], v[188:191], v[126:129]
	v_mfma_f32_16x16x32_bf16 v[122:125], v[168:171], v[188:191], v[122:125]
	v_mfma_f32_16x16x32_bf16 v[118:121], v[160:163], v[196:199], v[118:121]
	v_mfma_f32_16x16x32_bf16 v[114:117], v[168:171], v[196:199], v[114:117]
	v_mfma_f32_16x16x32_bf16 v[102:105], v[160:163], v[204:207], v[102:105]
	v_mfma_f32_16x16x32_bf16 v[98:101], v[168:171], v[204:207], v[98:101]
	v_mfma_f32_16x16x32_bf16 v[86:89], v[160:163], v[212:215], v[86:89]
	v_mfma_f32_16x16x32_bf16 v[82:85], v[168:171], v[212:215], v[82:85]
	s_setprio 0
	s_barrier
	s_add_i32 s22, 16, 0x14000
	s_add_i32 s19, s19, s9
	v_add_u32_e32 v155, s22, v152
	v_lshl_add_u64 v[232:233], s[66:67], 0, v[144:145]
	s_mov_b32 m0, s19
	ds_read_b128 v[216:219], v155
	ds_read_b128 v[220:223], v155 offset:1024
	ds_read_b128 v[224:227], v155 offset:2048
	ds_read_b128 v[228:231], v155 offset:3072
	global_load_lds_dwordx4 v[232:233], off
	v_lshl_add_u64 v[234:235], s[66:67], 0, v[140:141]
	s_add_i32 m0, s19, 0x2000
	s_nop 0
	global_load_lds_dwordx4 v[234:235], off
	s_barrier
	s_waitcnt lgkmcnt(0)
	s_setprio 1
	s_waitcnt lgkmcnt(0)
	v_mfma_f32_16x16x32_bf16 v[110:113], v[216:219], v[172:175], v[110:113]
	v_mfma_f32_16x16x32_bf16 v[106:109], v[224:227], v[172:175], v[106:109]
	v_mfma_f32_16x16x32_bf16 v[94:97], v[216:219], v[192:195], v[94:97]
	v_mfma_f32_16x16x32_bf16 v[90:93], v[224:227], v[192:195], v[90:93]
	v_mfma_f32_16x16x32_bf16 v[78:81], v[216:219], v[200:203], v[78:81]
	v_mfma_f32_16x16x32_bf16 v[74:77], v[224:227], v[200:203], v[74:77]
	v_mfma_f32_16x16x32_bf16 v[70:73], v[216:219], v[208:211], v[70:73]
	v_mfma_f32_16x16x32_bf16 v[66:69], v[224:227], v[208:211], v[66:69]
	v_mfma_f32_16x16x32_bf16 v[110:113], v[220:223], v[188:191], v[110:113]
	v_mfma_f32_16x16x32_bf16 v[106:109], v[228:231], v[188:191], v[106:109]
	v_mfma_f32_16x16x32_bf16 v[94:97], v[220:223], v[196:199], v[94:97]
	v_mfma_f32_16x16x32_bf16 v[90:93], v[228:231], v[196:199], v[90:93]
	v_mfma_f32_16x16x32_bf16 v[78:81], v[220:223], v[204:207], v[78:81]
	v_mfma_f32_16x16x32_bf16 v[74:77], v[228:231], v[204:207], v[74:77]
	v_mfma_f32_16x16x32_bf16 v[70:73], v[220:223], v[212:215], v[70:73]
	v_mfma_f32_16x16x32_bf16 v[66:69], v[228:231], v[212:215], v[66:69]
	s_setprio 0
	s_mov_b32 m0, s11
	v_lshl_add_u64 v[236:237], s[70:71], 0, v[146:147]
	s_barrier
; #define PG8_STAGE(bufoff, gbase, voff) do { _Pragma("unroll") for (int _i = 0; _i < 2; ++_i) \
;         __builtin_amdgcn_global_load_lds((const unsigned*)((const char*)(gbase) + (voff)[_i]), (LAS unsigned*)(lds + (bufoff) + ldsw + _i * 8192), 16, 0, 0); } while (0)
; #define PG8_LDA(dst, b, h) do { _Pragma("unroll") for (int m = 0; m < 4; ++m) _Pragma("unroll") for (int k = 0; k < 2; ++k) dst[m][k] = *(const LAS bf16x8*)(lds + PG8_SA(b, h) + aoff + m * 2048 + k * 1024); } while (0)
; #define PG8_LDB(dst, b, h) do { _Pragma("unroll") for (int n = 0; n < 2; ++n) _Pragma("unroll") for (int k = 0; k < 2; ++k) dst[n][k] = *(const LAS bf16x8*)(lds + PG8_SB(b, h) + boff + n * 2048 + k * 1024); } while (0)
; #define PG8_MMA(ai, bj, At, Bt) do { __builtin_amdgcn_s_setprio(1); _Pragma("unroll") for (int m = 0; m < 4; ++m) _Pragma("unroll") for (int n = 0; n < 2; ++n) _Pragma("unroll") for (int k = 0; k < 2; ++k) \
;         acc[ai][bj][m][n] = __builtin_amdgcn_mfma_f32_16x16x32_bf16(Bt[n][k], At[m][k], acc[ai][bj][m][n], 0, 0, 0); __builtin_amdgcn_s_setprio(0); } while (0)
; #define PG8_WAIT_V(n) asm volatile("s_waitcnt vmcnt(" #n ")" ::: "memory")
; #define PG8_WAIT_L(n) asm volatile("s_waitcnt lgkmcnt(" #n ")" ::: "memory")
; #define PG8_BAR __builtin_amdgcn_s_barrier()
; #define PG8_SCHED __builtin_amdgcn_sched_barrier(0)
; template <class Epi, class Sched>
; __device__ __forceinline__ void gemm_phase(LAS unsigned char* lds, const Gemm g, const Sched& S, const Epi& E) {
;     ...
;             PG8_LDA(At, 0, 1); PG8_STAGE(PG8_SA(0, 0), a2, voffA);
;             PG8_BAR; PG8_WAIT_L(0); PG8_MMA(1, 0, At, B0); PG8_BAR; PG8_SCHED;
;             PG8_STAGE(PG8_SB(0, 1), b2 + hstep, voffB);
;             PG8_WAIT_V(6); PG8_BAR; PG8_MMA(1, 1, At, B1); PG8_BAR;
;             PG8_LDB(B0, 1, 0); PG8_SCHED; PG8_LDA(At, 1, 0); PG8_STAGE(PG8_SA(0, 1), a2 + hstep, voffA);
;             PG8_WAIT_L(8); PG8_BAR; PG8_WAIT_L(0); PG8_MMA(0, 0, At, B0); PG8_BAR; PG8_SCHED;
;             PG8_LDB(B1, 1, 1); PG8_STAGE(PG8_SB(1, 0), b3, voffB);
	ds_read_b128 v[172:175], v154 offset:16384
	ds_read_b128 v[188:191], v154 offset:17408
	ds_read_b128 v[192:195], v154 offset:18432
	ds_read_b128 v[196:199], v154 offset:19456
	ds_read_b128 v[200:203], v154 offset:20480
	ds_read_b128 v[204:207], v154 offset:21504
	ds_read_b128 v[208:211], v154 offset:22528
	ds_read_b128 v[212:215], v154 offset:23552
	global_load_lds_dwordx4 v[236:237], off
	v_lshl_add_u64 v[238:239], s[70:71], 0, v[142:143]
	s_mov_b32 m0, s74
	s_nop 0
	global_load_lds_dwordx4 v[238:239], off
	s_barrier
	s_waitcnt lgkmcnt(0)
	s_setprio 1
	s_waitcnt lgkmcnt(0)
	v_mfma_f32_16x16x32_bf16 v[62:65], v[156:159], v[172:175], v[62:65]
	v_mfma_f32_16x16x32_bf16 v[58:61], v[164:167], v[172:175], v[58:61]
	v_mfma_f32_16x16x32_bf16 v[54:57], v[156:159], v[192:195], v[54:57]
	v_mfma_f32_16x16x32_bf16 v[50:53], v[164:167], v[192:195], v[50:53]
	v_mfma_f32_16x16x32_bf16 v[38:41], v[156:159], v[200:203], v[38:41]
	v_mfma_f32_16x16x32_bf16 v[34:37], v[164:167], v[200:203], v[34:37]
	v_mfma_f32_16x16x32_bf16 v[22:25], v[156:159], v[208:211], v[22:25]
	v_mfma_f32_16x16x32_bf16 v[18:21], v[164:167], v[208:211], v[18:21]
	v_mfma_f32_16x16x32_bf16 v[62:65], v[160:163], v[188:191], v[62:65]
	v_mfma_f32_16x16x32_bf16 v[58:61], v[168:171], v[188:191], v[58:61]
	v_mfma_f32_16x16x32_bf16 v[54:57], v[160:163], v[196:199], v[54:57]
	v_mfma_f32_16x16x32_bf16 v[50:53], v[168:171], v[196:199], v[50:53]
	v_mfma_f32_16x16x32_bf16 v[38:41], v[160:163], v[204:207], v[38:41]
	v_mfma_f32_16x16x32_bf16 v[34:37], v[168:171], v[204:207], v[34:37]
	v_mfma_f32_16x16x32_bf16 v[22:25], v[160:163], v[212:215], v[22:25]
	v_mfma_f32_16x16x32_bf16 v[18:21], v[168:171], v[212:215], v[18:21]
	s_setprio 0
	s_barrier
	s_add_u32 s20, s66, 0xb0000
	s_addc_u32 s21, s67, 0
	s_add_i32 s19, s22, s9
	v_lshl_add_u64 v[156:157], s[20:21], 0, v[144:145]
	s_mov_b32 m0, s19
	s_nop 0
	global_load_lds_dwordx4 v[156:157], off
	v_lshl_add_u64 v[156:157], s[20:21], 0, v[140:141]
	s_add_i32 m0, s19, 0x2000
	s_nop 0
	global_load_lds_dwordx4 v[156:157], off
	s_waitcnt vmcnt(6)
	s_barrier
	s_setprio 1
	v_mfma_f32_16x16x32_bf16 v[46:49], v[216:219], v[172:175], v[46:49]
	v_mfma_f32_16x16x32_bf16 v[42:45], v[224:227], v[172:175], v[42:45]
	v_mfma_f32_16x16x32_bf16 v[30:33], v[216:219], v[192:195], v[30:33]
	v_mfma_f32_16x16x32_bf16 v[26:29], v[224:227], v[192:195], v[26:29]
	v_mfma_f32_16x16x32_bf16 v[14:17], v[216:219], v[200:203], v[14:17]
	v_mfma_f32_16x16x32_bf16 v[10:13], v[224:227], v[200:203], v[10:13]
	v_mfma_f32_16x16x32_bf16 v[4:7], v[216:219], v[208:211], v[4:7]
	v_mfma_f32_16x16x32_bf16 v[0:3], v[224:227], v[208:211], v[0:3]
	v_mfma_f32_16x16x32_bf16 v[46:49], v[220:223], v[188:191], v[46:49]
	v_mfma_f32_16x16x32_bf16 v[42:45], v[228:231], v[188:191], v[42:45]
	v_mfma_f32_16x16x32_bf16 v[30:33], v[220:223], v[196:199], v[30:33]
	v_mfma_f32_16x16x32_bf16 v[26:29], v[228:231], v[196:199], v[26:29]
	v_mfma_f32_16x16x32_bf16 v[14:17], v[220:223], v[204:207], v[14:17]
	v_mfma_f32_16x16x32_bf16 v[10:13], v[228:231], v[204:207], v[10:13]
	v_mfma_f32_16x16x32_bf16 v[4:7], v[220:223], v[212:215], v[4:7]
	v_mfma_f32_16x16x32_bf16 v[0:3], v[228:231], v[212:215], v[0:3]
	s_setprio 0
	s_add_i32 s19, 16, 0x18000
	v_add_u32_e32 v155, s19, v152
	s_barrier
	ds_read_b128 v[156:159], v155
	ds_read_b128 v[160:163], v155 offset:1024
	ds_read_b128 v[164:167], v155 offset:2048
	ds_read_b128 v[168:171], v155 offset:3072
	s_add_u32 s20, s70, 0xb0000
	s_addc_u32 s21, s71, 0
	s_mov_b32 m0, s12
	v_lshl_add_u64 v[216:217], s[20:21], 0, v[146:147]
	ds_read_b128 v[172:175], v154 offset:32768
	ds_read_b128 v[188:191], v154 offset:33792
	ds_read_b128 v[192:195], v154 offset:34816
	ds_read_b128 v[196:199], v154 offset:35840
	ds_read_b128 v[200:203], v154 offset:36864
	ds_read_b128 v[204:207], v154 offset:37888
	ds_read_b128 v[208:211], v154 offset:38912
	ds_read_b128 v[212:215], v154 offset:39936
	global_load_lds_dwordx4 v[216:217], off
	v_lshl_add_u64 v[216:217], s[20:21], 0, v[142:143]
	s_mov_b32 m0, s13
	s_nop 0
	global_load_lds_dwordx4 v[216:217], off
	s_waitcnt lgkmcnt(8)
	s_barrier
	s_waitcnt lgkmcnt(0)
	s_setprio 1
	s_waitcnt lgkmcnt(0)
	v_mfma_f32_16x16x32_bf16 v[126:129], v[156:159], v[172:175], v[126:129]
	v_mfma_f32_16x16x32_bf16 v[122:125], v[164:167], v[172:175], v[122:125]
	v_mfma_f32_16x16x32_bf16 v[118:121], v[156:159], v[192:195], v[118:121]
	v_mfma_f32_16x16x32_bf16 v[114:117], v[164:167], v[192:195], v[114:117]
	v_mfma_f32_16x16x32_bf16 v[102:105], v[156:159], v[200:203], v[102:105]
	v_mfma_f32_16x16x32_bf16 v[98:101], v[164:167], v[200:203], v[98:101]
	v_mfma_f32_16x16x32_bf16 v[86:89], v[156:159], v[208:211], v[86:89]
	v_mfma_f32_16x16x32_bf16 v[82:85], v[164:167], v[208:211], v[82:85]
	v_mfma_f32_16x16x32_bf16 v[126:129], v[160:163], v[188:191], v[126:129]
	v_mfma_f32_16x16x32_bf16 v[122:125], v[168:171], v[188:191], v[122:125]
	v_mfma_f32_16x16x32_bf16 v[118:121], v[160:163], v[196:199], v[118:121]
	v_mfma_f32_16x16x32_bf16 v[114:117], v[168:171], v[196:199], v[114:117]
	v_mfma_f32_16x16x32_bf16 v[102:105], v[160:163], v[204:207], v[102:105]
	v_mfma_f32_16x16x32_bf16 v[98:101], v[168:171], v[204:207], v[98:101]
	v_mfma_f32_16x16x32_bf16 v[86:89], v[160:163], v[212:215], v[86:89]
	v_mfma_f32_16x16x32_bf16 v[82:85], v[168:171], v[212:215], v[82:85]
	s_setprio 0
	s_barrier
	s_add_i32 s22, 16, 0x1c000
	s_add_i32 s19, s19, s9
	v_add_u32_e32 v155, s22, v152
	v_lshl_add_u64 v[232:233], v[232:233], 0, s[94:95]
	s_mov_b32 m0, s19
	ds_read_b128 v[216:219], v155
	ds_read_b128 v[220:223], v155 offset:1024
	ds_read_b128 v[224:227], v155 offset:2048
	ds_read_b128 v[228:231], v155 offset:3072
	global_load_lds_dwordx4 v[232:233], off
	v_lshl_add_u64 v[232:233], v[234:235], 0, s[94:95]
	s_add_i32 m0, s19, 0x2000
	s_nop 0
	global_load_lds_dwordx4 v[232:233], off
	s_barrier
; #define PG8_STAGE(bufoff, gbase, voff) do { _Pragma("unroll") for (int _i = 0; _i < 2; ++_i) \
;         __builtin_amdgcn_global_load_lds((const unsigned*)((const char*)(gbase) + (voff)[_i]), (LAS unsigned*)(lds + (bufoff) + ldsw + _i * 8192), 16, 0, 0); } while (0)
; #define PG8_LDA(dst, b, h) do { _Pragma("unroll") for (int m = 0; m < 4; ++m) _Pragma("unroll") for (int k = 0; k < 2; ++k) dst[m][k] = *(const LAS bf16x8*)(lds + PG8_SA(b, h) + aoff + m * 2048 + k * 1024); } while (0)
; #define PG8_MMA(ai, bj, At, Bt) do { __builtin_amdgcn_s_setprio(1); _Pragma("unroll") for (int m = 0; m < 4; ++m) _Pragma("unroll") for (int n = 0; n < 2; ++n) _Pragma("unroll") for (int k = 0; k < 2; ++k) \
;         acc[ai][bj][m][n] = __builtin_amdgcn_mfma_f32_16x16x32_bf16(Bt[n][k], At[m][k], acc[ai][bj][m][n], 0, 0, 0); __builtin_amdgcn_s_setprio(0); } while (0)
; #define PG8_WAIT_V(n) asm volatile("s_waitcnt vmcnt(" #n ")" ::: "memory")
; #define PG8_WAIT_L(n) asm volatile("s_waitcnt lgkmcnt(" #n ")" ::: "memory")
; #define PG8_BAR __builtin_amdgcn_s_barrier()
; #define PG8_SCHED __builtin_amdgcn_sched_barrier(0)
; template <class Epi, class Sched>
; __device__ __forceinline__ void gemm_phase(LAS unsigned char* lds, const Gemm g, const Sched& S, const Epi& E) {
;     ...
;             PG8_BAR; PG8_WAIT_L(0); PG8_MMA(0, 1, At, B1); PG8_BAR;
;             PG8_LDA(At, 1, 1); PG8_STAGE(PG8_SA(1, 0), a3, voffA);
;             PG8_BAR; PG8_WAIT_L(0); PG8_MMA(1, 0, At, B0); PG8_BAR; PG8_SCHED;
;             PG8_STAGE(PG8_SB(1, 1), b3 + hstep, voffB);
;             PG8_WAIT_V(6); PG8_BAR; PG8_MMA(1, 1, At, B1); PG8_BAR;
;         }
	s_waitcnt lgkmcnt(0)
	s_setprio 1
	s_waitcnt lgkmcnt(0)
	v_mfma_f32_16x16x32_bf16 v[110:113], v[216:219], v[172:175], v[110:113]
	v_mfma_f32_16x16x32_bf16 v[106:109], v[224:227], v[172:175], v[106:109]
	v_mfma_f32_16x16x32_bf16 v[94:97], v[216:219], v[192:195], v[94:97]
	v_mfma_f32_16x16x32_bf16 v[90:93], v[224:227], v[192:195], v[90:93]
	v_mfma_f32_16x16x32_bf16 v[78:81], v[216:219], v[200:203], v[78:81]
	v_mfma_f32_16x16x32_bf16 v[74:77], v[224:227], v[200:203], v[74:77]
	v_mfma_f32_16x16x32_bf16 v[70:73], v[216:219], v[208:211], v[70:73]
	v_mfma_f32_16x16x32_bf16 v[66:69], v[224:227], v[208:211], v[66:69]
	v_mfma_f32_16x16x32_bf16 v[110:113], v[220:223], v[188:191], v[110:113]
	v_mfma_f32_16x16x32_bf16 v[106:109], v[228:231], v[188:191], v[106:109]
	v_mfma_f32_16x16x32_bf16 v[94:97], v[220:223], v[196:199], v[94:97]
	v_mfma_f32_16x16x32_bf16 v[90:93], v[228:231], v[196:199], v[90:93]
	v_mfma_f32_16x16x32_bf16 v[78:81], v[220:223], v[204:207], v[78:81]
	v_mfma_f32_16x16x32_bf16 v[74:77], v[228:231], v[204:207], v[74:77]
	v_mfma_f32_16x16x32_bf16 v[70:73], v[220:223], v[212:215], v[70:73]
	v_mfma_f32_16x16x32_bf16 v[66:69], v[228:231], v[212:215], v[66:69]
	s_setprio 0
	s_mov_b32 m0, s14
	v_lshl_add_u64 v[232:233], v[236:237], 0, s[94:95]
	s_barrier
	ds_read_b128 v[172:175], v154 offset:49152
	ds_read_b128 v[188:191], v154 offset:50176
	ds_read_b128 v[192:195], v154 offset:51200
	ds_read_b128 v[196:199], v154 offset:52224
	ds_read_b128 v[200:203], v154 offset:53248
	ds_read_b128 v[204:207], v154 offset:54272
	ds_read_b128 v[208:211], v154 offset:55296
	ds_read_b128 v[212:215], v154 offset:56320
	global_load_lds_dwordx4 v[232:233], off
	v_lshl_add_u64 v[232:233], v[238:239], 0, s[94:95]
	s_mov_b32 m0, s15
	s_nop 0
	global_load_lds_dwordx4 v[232:233], off
	s_barrier
	s_waitcnt lgkmcnt(0)
	s_setprio 1
	s_waitcnt lgkmcnt(0)
	v_mfma_f32_16x16x32_bf16 v[62:65], v[156:159], v[172:175], v[62:65]
	v_mfma_f32_16x16x32_bf16 v[58:61], v[164:167], v[172:175], v[58:61]
	v_mfma_f32_16x16x32_bf16 v[54:57], v[156:159], v[192:195], v[54:57]
	v_mfma_f32_16x16x32_bf16 v[50:53], v[164:167], v[192:195], v[50:53]
	v_mfma_f32_16x16x32_bf16 v[38:41], v[156:159], v[200:203], v[38:41]
	v_mfma_f32_16x16x32_bf16 v[34:37], v[164:167], v[200:203], v[34:37]
	v_mfma_f32_16x16x32_bf16 v[22:25], v[156:159], v[208:211], v[22:25]
	v_mfma_f32_16x16x32_bf16 v[18:21], v[164:167], v[208:211], v[18:21]
	v_mfma_f32_16x16x32_bf16 v[62:65], v[160:163], v[188:191], v[62:65]
	v_mfma_f32_16x16x32_bf16 v[58:61], v[168:171], v[188:191], v[58:61]
	v_mfma_f32_16x16x32_bf16 v[54:57], v[160:163], v[196:199], v[54:57]
	v_mfma_f32_16x16x32_bf16 v[50:53], v[168:171], v[196:199], v[50:53]
	v_mfma_f32_16x16x32_bf16 v[38:41], v[160:163], v[204:207], v[38:41]
	v_mfma_f32_16x16x32_bf16 v[34:37], v[168:171], v[204:207], v[34:37]
	v_mfma_f32_16x16x32_bf16 v[22:25], v[160:163], v[212:215], v[22:25]
	v_mfma_f32_16x16x32_bf16 v[18:21], v[168:171], v[212:215], v[18:21]
	s_setprio 0
	s_barrier
	s_add_u32 s20, s66, 0xb0080
	s_addc_u32 s21, s67, 0
	s_add_i32 s19, s22, s9
	v_lshl_add_u64 v[156:157], s[20:21], 0, v[144:145]
	s_mov_b32 m0, s19
	s_nop 0
	global_load_lds_dwordx4 v[156:157], off
	v_lshl_add_u64 v[156:157], s[20:21], 0, v[140:141]
	s_add_i32 m0, s19, 0x2000
	s_nop 0
	global_load_lds_dwordx4 v[156:157], off
	s_waitcnt vmcnt(6)
	s_barrier
	s_setprio 1
	v_mfma_f32_16x16x32_bf16 v[46:49], v[216:219], v[172:175], v[46:49]
	v_mfma_f32_16x16x32_bf16 v[42:45], v[224:227], v[172:175], v[42:45]
	v_mfma_f32_16x16x32_bf16 v[30:33], v[216:219], v[192:195], v[30:33]
	v_mfma_f32_16x16x32_bf16 v[26:29], v[224:227], v[192:195], v[26:29]
	v_mfma_f32_16x16x32_bf16 v[14:17], v[216:219], v[200:203], v[14:17]
	v_mfma_f32_16x16x32_bf16 v[10:13], v[224:227], v[200:203], v[10:13]
	v_mfma_f32_16x16x32_bf16 v[4:7], v[216:219], v[208:211], v[4:7]
	v_mfma_f32_16x16x32_bf16 v[0:3], v[224:227], v[208:211], v[0:3]
	v_mfma_f32_16x16x32_bf16 v[46:49], v[220:223], v[188:191], v[46:49]
	v_mfma_f32_16x16x32_bf16 v[42:45], v[228:231], v[188:191], v[42:45]
	v_mfma_f32_16x16x32_bf16 v[30:33], v[220:223], v[196:199], v[30:33]
	v_mfma_f32_16x16x32_bf16 v[26:29], v[228:231], v[196:199], v[26:29]
	v_mfma_f32_16x16x32_bf16 v[14:17], v[220:223], v[204:207], v[14:17]
	v_mfma_f32_16x16x32_bf16 v[10:13], v[228:231], v[204:207], v[10:13]
	v_mfma_f32_16x16x32_bf16 v[4:7], v[220:223], v[212:215], v[4:7]
	v_mfma_f32_16x16x32_bf16 v[0:3], v[228:231], v[212:215], v[0:3]
	s_setprio 0
	s_add_i32 s18, s18, 2
	s_add_u32 s16, s16, 0x100
	s_addc_u32 s17, s17, 0
	s_cmp_gt_u32 s18, 41
	s_mov_b64 s[42:43], s[72:73]
	s_barrier
	s_cbranch_scc0 .LBB0_825
; __device__ __forceinline__ unsigned pk_bf16(float a, float b) { f32x2 v = {a, b}; bf2_t r = __builtin_convertvector(v, bf2_t); return __builtin_bit_cast(unsigned, r); }
; #define PG8_WAIT_V(n) asm volatile("s_waitcnt vmcnt(" #n ")" ::: "memory")
; #define PG8_BAR __builtin_amdgcn_s_barrier()
;     __device__ __forceinline__ void operator()(const f32x4 (&acc)[2][2][4][2], const Unit& u, int wr, int wc, int fr, int fq) const {
;         const int row0 = u.pm * BM + wr * 64 + fr; int colt = u.pn * BM; bf16_t* base = O;
;         if (split_cols) { const int t = colt / split_cols; base += (size_t)t * split_stride; colt -= t * split_cols; }
;         const int col0 = colt + wc * 32 + 8 * fq;
; #pragma unroll
;         for (int ai = 0; ai < 2; ++ai)
; #pragma unroll
;             for (int m = 0; m < 4; ++m) { const int row = row0 + ai * HALF + m * 16;
;                 bf16_t* rowp = slot_stride ? base + (size_t)(colt >> 7) * slot_stride + (size_t)row * 128 + wc * 32 + 8 * fq : base + (size_t)row * ldc + col0;
; #pragma unroll
;                 for (int bj = 0; bj < 2; ++bj) { const f32x4 v0 = acc[ai][bj][m][0], v1 = acc[ai][bj][m][1];
;                     u32x4 w; w.x = pk_bf16(v0[0], v0[1]); w.y = pk_bf16(v0[2], v0[3]); w.z = pk_bf16(v1[0], v1[1]); w.w = pk_bf16(v1[2], v1[3]);
;                     *(u32x4*)(rowp + (slot_stride ? (size_t)bj * slot_stride : (size_t)bj * HALF)) = w; } }
; template <class Epi, class Sched>
; __device__ __forceinline__ void gemm_phase(LAS unsigned char* lds, const Gemm g, const Sched& S, const Epi& E) {
;     ...
;         E(acc, cur, wr, wc, fr, fq); S.done(cur);
;         if (!has_next) break;
; #pragma unroll
;         for (int a = 0; a < 2; ++a)
; #pragma unroll
;             for (int b = 0; b < 2; ++b)
; #pragma unroll
;                 for (int m = 0; m < 4; ++m)
; #pragma unroll
;                     for (int n = 0; n < 2; ++n) acc[a][b][m][n] = (f32x4){0.f, 0.f, 0.f, 0.f};
;         cur = nxt; cA = nA; cB = nB; ++ui;
;     }
;     PG8_WAIT_V(0);
;     if (wr == 0) PG8_BAR;
	v_lshl_add_u32 v156, s78, 8, v9
	v_lshl_or_b32 v158, s75, 8, v153
	v_readlane_b32 s16, v244, 38
	v_ashrrev_i32_e32 v159, 31, v158
	v_readlane_b32 s17, v244, 39
	v_ashrrev_i32_e32 v157, 31, v156
	v_lshlrev_b64 v[160:161], 11, v[156:157]
	v_lshl_add_u64 v[158:159], v[158:159], 1, s[16:17]
	v_lshl_add_u64 v[160:161], v[158:159], 0, v[160:161]
	s_mov_b64 s[16:17], 0x40000
	v_cvt_pk_bf16_f32 v70, v70, v71
	v_cvt_pk_bf16_f32 v71, v72, v73
	v_cvt_pk_bf16_f32 v72, v66, v67
	v_lshl_add_u64 v[66:67], v[160:161], 0, s[16:17]
	s_mov_b32 s16, 0x40000
	v_cvt_pk_bf16_f32 v62, v62, v63
	v_cvt_pk_bf16_f32 v63, v64, v65
	v_cvt_pk_bf16_f32 v64, v58, v59
	v_add_co_u32_e32 v58, vcc, s16, v160
	v_cvt_pk_bf16_f32 v46, v46, v47
	v_cvt_pk_bf16_f32 v47, v48, v49
	v_cvt_pk_bf16_f32 v48, v42, v43
	v_cvt_pk_bf16_f32 v49, v44, v45
	s_mov_b64 s[16:17], 0x48000
	v_addc_co_u32_e32 v59, vcc, 0, v161, vcc
	global_store_dwordx4 v[66:67], v[46:49], off offset:256
	v_cvt_pk_bf16_f32 v30, v30, v31
	v_cvt_pk_bf16_f32 v31, v32, v33
	v_lshl_add_u64 v[46:47], v[160:161], 0, s[16:17]
	s_mov_b32 s16, 0x48000
	v_add_co_u32_e32 v48, vcc, s16, v160
	v_cvt_pk_bf16_f32 v32, v26, v27
	v_cvt_pk_bf16_f32 v33, v28, v29
	s_mov_b64 s[16:17], 0x50000
	v_cvt_pk_bf16_f32 v110, v110, v111
	v_cvt_pk_bf16_f32 v111, v112, v113
	v_cvt_pk_bf16_f32 v112, v106, v107
	v_or_b32_e32 v106, 16, v156
	v_addc_co_u32_e32 v49, vcc, 0, v161, vcc
	global_store_dwordx4 v[46:47], v[30:33], off offset:256
	v_ashrrev_i32_e32 v107, 31, v106
	v_cvt_pk_bf16_f32 v94, v94, v95
	v_lshl_add_u64 v[30:31], v[160:161], 0, s[16:17]
	s_mov_b32 s16, 0x50000
	v_cvt_pk_bf16_f32 v95, v96, v97
	v_cvt_pk_bf16_f32 v96, v90, v91
	v_or_b32_e32 v90, 32, v156
	v_add_co_u32_e32 v32, vcc, s16, v160
	v_cvt_pk_bf16_f32 v14, v14, v15
	v_cvt_pk_bf16_f32 v15, v16, v17
	v_cvt_pk_bf16_f32 v16, v10, v11
	v_cvt_pk_bf16_f32 v17, v12, v13
	s_mov_b64 s[16:17], 0x58000
	v_cvt_pk_bf16_f32 v113, v108, v109
	v_lshlrev_b64 v[106:107], 11, v[106:107]
	v_ashrrev_i32_e32 v91, 31, v90
	v_cvt_pk_bf16_f32 v78, v78, v79
	v_cvt_pk_bf16_f32 v79, v80, v81
	v_cvt_pk_bf16_f32 v80, v74, v75
	v_or_b32_e32 v74, 48, v156
	v_addc_co_u32_e32 v33, vcc, 0, v161, vcc
	global_store_dwordx4 v[30:31], v[14:17], off offset:256
	global_store_dwordx4 v[160:161], v[110:113], off offset:256
	v_cvt_pk_bf16_f32 v97, v92, v93
	v_lshl_add_u64 v[14:15], v[160:161], 0, s[16:17]
	s_mov_b32 s16, 0x58000
	v_lshl_add_u64 v[110:111], v[158:159], 0, v[106:107]
	v_lshlrev_b64 v[90:91], 11, v[90:91]
	v_ashrrev_i32_e32 v75, 31, v74
	v_add_co_u32_e32 v16, vcc, s16, v160
	global_store_dwordx4 v[110:111], v[94:97], off offset:256
	v_cvt_pk_bf16_f32 v81, v76, v77
	v_lshlrev_b64 v[74:75], 11, v[74:75]
	v_lshl_add_u64 v[94:95], v[158:159], 0, v[90:91]
	v_addc_co_u32_e32 v17, vcc, 0, v161, vcc
	v_readlane_b32 s70, v244, 55
	v_cvt_pk_bf16_f32 v126, v126, v127
	v_cvt_pk_bf16_f32 v127, v128, v129
	v_cvt_pk_bf16_f32 v128, v122, v123
	v_cvt_pk_bf16_f32 v129, v124, v125
	v_cvt_pk_bf16_f32 v106, v118, v119
	v_cvt_pk_bf16_f32 v107, v120, v121
	v_cvt_pk_bf16_f32 v108, v114, v115
	v_cvt_pk_bf16_f32 v109, v116, v117
	v_cvt_pk_bf16_f32 v90, v102, v103
	v_cvt_pk_bf16_f32 v91, v104, v105
	v_cvt_pk_bf16_f32 v92, v98, v99
	v_cvt_pk_bf16_f32 v93, v100, v101
	global_store_dwordx4 v[94:95], v[78:81], off offset:256
	v_cvt_pk_bf16_f32 v76, v82, v83
	v_cvt_pk_bf16_f32 v77, v84, v85
	v_lshl_add_u64 v[78:79], v[158:159], 0, v[74:75]
	v_cvt_pk_bf16_f32 v74, v86, v87
	v_cvt_pk_bf16_f32 v75, v88, v89
	v_cvt_pk_bf16_f32 v73, v68, v69
	v_cvt_pk_bf16_f32 v65, v60, v61
	v_cvt_pk_bf16_f32 v42, v54, v55
	v_cvt_pk_bf16_f32 v43, v56, v57
	v_cvt_pk_bf16_f32 v44, v50, v51
	v_cvt_pk_bf16_f32 v45, v52, v53
	v_cvt_pk_bf16_f32 v26, v38, v39
	v_cvt_pk_bf16_f32 v27, v40, v41
	v_cvt_pk_bf16_f32 v28, v34, v35
	v_cvt_pk_bf16_f32 v29, v36, v37
	v_cvt_pk_bf16_f32 v10, v22, v23
	v_cvt_pk_bf16_f32 v11, v24, v25
	v_cvt_pk_bf16_f32 v12, v18, v19
	v_cvt_pk_bf16_f32 v13, v20, v21
	v_cvt_pk_bf16_f32 v4, v4, v5
	v_cvt_pk_bf16_f32 v5, v6, v7
	v_cvt_pk_bf16_f32 v6, v0, v1
	v_cvt_pk_bf16_f32 v7, v2, v3
	s_and_b64 vcc, exec, s[38:39]
	s_mov_b32 s75, s85
	s_mov_b32 s78, s88
	s_mov_b64 s[72:73], s[0:1]
	s_mov_b64 s[42:43], s[40:41]
	v_readlane_b32 s71, v244, 56
	global_store_dwordx4 v[160:161], v[126:129], off
	global_store_dwordx4 v[110:111], v[106:109], off
	global_store_dwordx4 v[94:95], v[90:93], off
	global_store_dwordx4 v[78:79], v[74:77], off
	global_store_dwordx4 v[78:79], v[70:73], off offset:256
	global_store_dwordx4 v[58:59], v[62:65], off
	global_store_dwordx4 v[48:49], v[42:45], off
	global_store_dwordx4 v[32:33], v[26:29], off
	global_store_dwordx4 v[16:17], v[10:13], off
	global_store_dwordx4 v[14:15], v[4:7], off offset:256
	s_cbranch_vccz .LBB0_818
	s_waitcnt vmcnt(0)
	v_readlane_b32 s16, v244, 51
	s_cmpk_gt_u32 s6, 0xff
	v_readlane_b32 s17, v244, 52
	s_cbranch_scc1 .LBB0_829
	s_barrier
